# p5x + P2 decode page stream: first-KB V pieces via LDS-DMA + ds_read (25% of page bytes off the VGPR load path), both groups
# speedup vs baseline: 1.0028x; 1.0028x over previous
.LBB0_624:
	v_readlane_b32 s4, v245, 2
	v_readlane_b32 s7, v245, 5
	s_bitcmp0_b32 s7, 5
	v_readlane_b32 s5, v245, 3
	v_readlane_b32 s6, v245, 4
	s_cbranch_scc1 .LBB0_635
	v_lshrrev_b32_e32 v246, 6, v0
	v_and_b32_e32 v247, 63, v0
	s_nop 0
	v_readfirstlane_b32 s98, v246
	v_lshlrev_b32_e32 v247, 4, v247
	s_lshl_b32 s98, s98, 13
	s_add_i32 s98, s98, 0x9000
	v_add_u32_e32 v246, s98, v247
	s_and_b32 s33, s95, -2
	s_ashr_i32 s1, s95, 31
	s_add_i32 s0, s33, s1
	s_xor_b32 s2, s0, s1
	v_cvt_f32_u32_e32 v1, s2
	v_readlane_b32 s0, v245, 54
	s_lshl_b32 s0, s0, 1
	s_sub_i32 s3, s33, s0
	v_rcp_iflag_f32_e32 v1, v1
	s_addk_i32 s3, 0x6ef
	s_ashr_i32 s4, s3, 31
	s_sub_i32 s5, 0, s2
	v_mul_f32_e32 v1, 0x4f7ffffe, v1
	v_cvt_u32_f32_e32 v1, v1
	s_xor_b32 s56, s4, s1
	s_abs_i32 s3, s3
	v_mov_b32_e32 v131, v0
	v_readfirstlane_b32 s1, v1
	s_mul_i32 s5, s5, s1
	s_mul_hi_u32 s4, s1, s5
	s_add_i32 s1, s1, s4
	s_mul_hi_u32 s1, s3, s1
	s_mul_i32 s4, s1, s2
	s_sub_i32 s3, s3, s4
	s_add_i32 s5, s1, 1
	s_sub_i32 s4, s3, s2
	s_cmp_ge_u32 s3, s2
	s_cselect_b32 s1, s5, s1
	s_cselect_b32 s3, s4, s3
	s_add_i32 s4, s1, 1
	s_cmp_ge_u32 s3, s2
	s_cselect_b32 s1, s4, s1
	s_xor_b32 s57, s1, s56
	s_sub_i32 s68, s57, s56
	s_cmp_lt_i32 s68, 1
	v_readfirstlane_b32 s1, v131
	s_cbranch_scc1 .LBB0_635
	s_add_u32 s2, s96, 0xce00000
	s_addc_u32 s3, s97, 0
	s_ashr_i32 s58, s1, 6
	s_ashr_i32 s1, s0, 31
	v_readlane_b32 s8, v245, 9
	s_add_i32 s6, s0, 0x110
	s_lshl_b64 s[0:1], s[0:1], 2
	v_readlane_b32 s10, v245, 11
	v_readlane_b32 s11, v245, 12
	s_add_u32 s0, s10, s0
	s_addc_u32 s1, s11, s1
	v_mov_b32_e32 v187, 0
	global_load_dword v1, v187, s[0:1] offset:1088
	s_cmp_lg_u32 s68, 1
	s_cselect_b32 s4, s33, 0
	s_ashr_i32 s5, s4, 31
	s_lshl_b64 s[4:5], s[4:5], 2
	s_add_u32 s0, s0, s4
	v_readlane_b32 s16, v245, 17
	v_readlane_b32 s20, v245, 21
	s_addc_u32 s1, s1, s5
	s_lshl_b32 s4, s58, 4
	v_readlane_b32 s9, v245, 10
	v_readlane_b32 s17, v245, 18
	v_readlane_b32 s21, v245, 22
	s_ashr_i32 s8, s6, 4
	global_load_dword v133, v187, s[0:1] offset:1088
	s_or_b32 s16, s4, 1
	s_or_b32 s20, s4, 2
	s_or_b32 s24, s4, 3
	s_or_b32 s30, s4, 4
	s_or_b32 s36, s4, 5
	s_or_b32 s60, s4, 6
	s_or_b32 s0, s4, 7
	s_ashr_i32 s5, s4, 31
	s_ashr_i32 s9, s8, 31
	s_ashr_i32 s17, s16, 31
	s_ashr_i32 s21, s20, 31
	s_ashr_i32 s25, s24, 31
	s_ashr_i32 s31, s30, 31
	s_ashr_i32 s37, s36, 31
	s_ashr_i32 s61, s60, 31
	s_ashr_i32 s1, s0, 31
	s_lshl_b64 s[6:7], s[4:5], 9
	s_lshl_b64 s[8:9], s[8:9], 10
	s_lshl_b64 s[38:39], s[16:17], 9
	s_lshl_b64 s[40:41], s[20:21], 9
	s_lshl_b64 s[42:43], s[24:25], 9
	s_lshl_b64 s[44:45], s[30:31], 9
	s_lshl_b64 s[46:47], s[36:37], 9
	s_lshl_b64 s[48:49], s[60:61], 9
	s_lshl_b64 s[50:51], s[0:1], 9
	v_and_b32_e32 v130, 63, v131
	s_add_u32 s8, s2, s8
	v_lshlrev_b32_e32 v186, 3, v130
	s_addc_u32 s9, s3, s9
	s_waitcnt vmcnt(0)
	v_lshl_add_u64 v[34:35], s[8:9], 0, v[186:187]
	v_readlane_b32 s12, v245, 13
	v_readlane_b32 s13, v245, 14
	v_lshlrev_b32_e32 v132, 4, v130
	v_readlane_b32 s14, v245, 15
	v_readlane_b32 s15, v245, 16
	v_readlane_b32 s18, v245, 19
	v_readlane_b32 s19, v245, 20
	v_readlane_b32 s22, v245, 23
	v_readlane_b32 s23, v245, 24
	s_mov_b32 s94, s85
	s_mov_b32 s69, 0x1000000
	v_add_co_u32_e32 v36, vcc, s69, v34
	v_bfe_u32 v134, v131, 2, 4
	s_nop 0
	v_addc_co_u32_e32 v37, vcc, 0, v35, vcc
	v_ashrrev_i32_e32 v137, 6, v131
	v_bfe_u32 v139, v131, 5, 1
	v_ashrrev_i32_e32 v138, 7, v131
	v_lshlrev_b32_e32 v135, 1, v139
	v_and_b32_e32 v136, 31, v131
	v_lshl_add_u64 v[188:189], s[2:3], 0, v[186:187]
	v_lshlrev_b32_e32 v186, 4, v136
	s_mov_b64 s[2:3], 0x23200020
	v_lshl_add_u32 v215, v131, 2, 0
	v_lshlrev_b32_e32 v216, 4, v130
	s_mov_b32 s90, 0xff800000
	v_readfirstlane_b32 s8, v1
	s_ashr_i32 s9, s8, 31
	s_lshl_b64 s[8:9], s[8:9], 18
	s_add_u32 s10, s80, s8
	s_addc_u32 s11, s81, s9
	s_lshl_b64 s[12:13], s[0:1], 11
	s_add_u32 s0, s10, s12
	s_addc_u32 s1, s11, s13
	global_load_dwordx4 v[6:9], v132, s[0:1] offset:1024 nt
	s_add_i32 m0, s98, 0x1c00
	s_nop 0
	global_load_lds_dwordx4 v132, s[0:1] nt
	s_add_u32 s0, s78, s8
	s_addc_u32 s1, s79, s9
	s_add_u32 s8, s0, s12
	s_addc_u32 s9, s1, s13
	s_lshl_b64 s[14:15], s[4:5], 11
	s_add_u32 s12, s0, s14
	s_addc_u32 s13, s1, s15
	s_lshl_b64 s[18:19], s[16:17], 11
	s_add_u32 s16, s0, s18
	s_addc_u32 s17, s1, s19
	s_lshl_b64 s[22:23], s[20:21], 11
	s_add_u32 s20, s0, s22
	s_addc_u32 s21, s1, s23
	s_lshl_b64 s[28:29], s[24:25], 11
	s_add_u32 s24, s0, s28
	global_load_dwordx4 v[26:29], v132, s[8:9] offset:1024 nt
	global_load_dwordx4 v[30:33], v132, s[8:9] nt
	s_addc_u32 s25, s1, s29
	s_lshl_b64 s[8:9], s[30:31], 11
	s_add_u32 s30, s0, s8
	s_addc_u32 s31, s1, s9
	s_lshl_b64 s[36:37], s[36:37], 11
	s_add_u32 s84, s0, s36
	s_addc_u32 s85, s1, s37
	s_lshl_b64 s[60:61], s[60:61], 11
	global_load_dwordx4 v[62:65], v132, s[84:85] nt
	global_load_dwordx4 v[58:61], v132, s[84:85] offset:1024 nt
	s_add_u32 s84, s0, s60
	s_addc_u32 s85, s1, s61
	s_add_u32 s60, s10, s60
	s_addc_u32 s61, s11, s61
	s_add_u32 s36, s10, s36
	s_addc_u32 s37, s11, s37
	global_load_dwordx4 v[54:57], v132, s[84:85] nt
	global_load_dwordx4 v[50:53], v132, s[84:85] offset:1024 nt
	global_load_dwordx4 v[22:25], v132, s[60:61] offset:1024 nt
	s_add_i32 m0, s98, 0x1800
	s_nop 0
	global_load_lds_dwordx4 v132, s[60:61] nt
	global_load_dwordx4 v[18:21], v132, s[36:37] offset:1024 nt
	s_add_i32 m0, s98, 0x1400
	s_nop 0
	global_load_lds_dwordx4 v132, s[36:37] nt
	s_add_u32 s36, s10, s8
	s_addc_u32 s37, s11, s9
	s_mov_b64 s[8:9], 0x1000000
	v_lshl_add_u64 v[34:35], v[34:35], 0, s[8:9]
	global_load_dwordx2 v[34:35], v[34:35], off offset:512
	s_nop 0
	global_load_dwordx2 v[36:37], v[36:37], off
	s_nop 0
	global_load_dwordx4 v[66:69], v132, s[36:37] offset:1024 nt
	s_add_i32 m0, s98, 0x1000
	s_nop 0
	global_load_lds_dwordx4 v132, s[36:37] nt
	s_add_u32 s28, s10, s28
	s_addc_u32 s29, s11, s29
	s_add_u32 s22, s10, s22
	s_addc_u32 s23, s11, s23
	s_add_u32 s18, s10, s18
	s_addc_u32 s19, s11, s19
	s_add_u32 s14, s10, s14
	s_addc_u32 s15, s11, s15
	global_load_dwordx4 v[118:121], v132, s[30:31] nt
	global_load_dwordx4 v[114:117], v132, s[30:31] offset:1024 nt
	s_lshl_b32 s5, s58, 12
	s_add_i32 s5, s5, 0
	s_mulk_i32 s58, 0xf020
	v_add_u32_e32 v1, s5, v132
	s_add_i32 s5, s5, s58
	v_add_u32_e32 v214, s5, v134
	v_lshlrev_b32_e32 v134, 2, v137
	v_and_b32_e32 v134, 4, v134
	s_movk_i32 s37, 0x88
	v_add3_u32 v134, v138, v134, v135
	v_mul_lo_u32 v134, v134, s37
	v_ashrrev_i32_e32 v135, 31, v134
	v_lshl_add_u64 v[134:135], v[134:135], 2, v[186:187]
	v_lshl_add_u64 v[190:191], v[134:135], 0, s[2:3]
	v_readlane_b32 s2, v245, 51
	s_lshl_b32 s2, s2, 1
	v_readlane_b32 s3, v245, 52
	s_andn2_b32 s2, s2, 63
	s_lshl_b32 s3, s3, 1
	v_lshlrev_b32_e32 v134, 1, v137
	s_or_b32 s2, s2, s3
	v_and_or_b32 v134, v134, 2, v139
	s_add_i32 s86, s2, 0x110
	v_lshl_add_u32 v134, v134, 1, v138
	s_lshl_b32 s85, s33, 1
	s_movk_i32 s36, 0x100
	v_mul_lo_u32 v140, v131, s37
	s_ashr_i32 s87, s86, 31
	s_mul_i32 s3, s86, 0x1100
	v_lshl_add_u32 v186, v134, 2, 0
	v_and_b32_e32 v134, -8, v131
	s_mul_hi_i32 s2, s86, 0x1100
	v_lshl_add_u32 v137, v137, 10, 0
	v_mov_b32_e32 v135, v187
	s_mov_b32 s84, 2
	v_add_u32_e32 v217, v137, v132
	v_readfirstlane_b32 s26, v133
	s_waitcnt vmcnt(5)
	v_lshlrev_b32_e32 v219, 16, v34
	v_and_b32_e32 v220, 0xffff0000, v34
	v_lshlrev_b32_e32 v198, 16, v35
	v_and_b32_e32 v199, 0xffff0000, v35
	s_waitcnt vmcnt(4)
	v_lshlrev_b32_e32 v221, 16, v36
	v_and_b32_e32 v222, 0xffff0000, v36
	v_lshlrev_b32_e32 v200, 16, v37
	v_and_b32_e32 v201, 0xffff0000, v37
	global_load_dwordx4 v[74:77], v132, s[28:29] offset:1024 nt
	s_add_i32 m0, s98, 0xc00
	s_nop 0
	global_load_lds_dwordx4 v132, s[28:29] nt
	global_load_dwordx4 v[94:97], v132, s[24:25] nt
	global_load_dwordx4 v[90:93], v132, s[24:25] offset:1024 nt
	global_load_dwordx4 v[78:81], v132, s[22:23] offset:1024 nt
	s_add_i32 m0, s98, 0x800
	s_nop 0
	global_load_lds_dwordx4 v132, s[22:23] nt
	global_load_dwordx4 v[102:105], v132, s[20:21] nt
	global_load_dwordx4 v[98:101], v132, s[20:21] offset:1024 nt
	global_load_dwordx4 v[82:85], v132, s[18:19] offset:1024 nt
	s_add_i32 m0, s98, 0x400
	s_nop 0
	global_load_lds_dwordx4 v132, s[18:19] nt
	global_load_dwordx4 v[110:113], v132, s[16:17] nt
	global_load_dwordx4 v[106:109], v132, s[16:17] offset:1024 nt
	global_load_dwordx4 v[86:89], v132, s[14:15] offset:1024 nt
	s_add_i32 m0, s98, 0x0
	s_nop 0
	global_load_lds_dwordx4 v132, s[14:15] nt
	global_load_dwordx4 v[126:129], v132, s[12:13] nt
	global_load_dwordx4 v[122:125], v132, s[12:13] offset:1024 nt
	s_or_b32 s12, s4, 8
	s_ashr_i32 s13, s12, 31
	s_lshl_b64 s[14:15], s[12:13], 9
	s_or_b32 s12, s4, 9
	s_ashr_i32 s13, s12, 31
	s_lshl_b64 s[16:17], s[12:13], 9
	s_or_b32 s12, s4, 10
	s_ashr_i32 s13, s12, 31
	s_lshl_b64 s[18:19], s[12:13], 9
	s_or_b32 s12, s4, 11
	s_ashr_i32 s13, s12, 31
	s_lshl_b64 s[20:21], s[12:13], 9
	s_or_b32 s12, s4, 13
	s_ashr_i32 s13, s12, 31
	s_or_b32 s22, s4, 12
	s_lshl_b64 s[24:25], s[12:13], 9
	s_or_b32 s12, s4, 14
	s_or_b32 s4, s4, 15
	s_ashr_i32 s23, s22, 31
	s_ashr_i32 s13, s12, 31
	s_ashr_i32 s5, s4, 31
	s_lshl_b64 s[22:23], s[22:23], 9
	s_lshl_b64 s[28:29], s[12:13], 9
	s_lshl_b64 s[30:31], s[4:5], 9
	s_add_u32 s12, s96, s3
	v_cmp_eq_u32_e64 s[4:5], s36, v134
	v_add_u32_e32 v134, 0xffff7800, v140
	s_addc_u32 s13, s97, s2
	v_cmp_gt_i32_e64 s[2:3], s36, v131
	s_sub_i32 s88, s56, s57
	v_lshlrev_b64 v[192:193], 2, v[134:135]
	s_lshl_b64 s[14:15], s[14:15], 2
	s_lshl_b64 s[16:17], s[16:17], 2
	s_lshl_b64 s[18:19], s[18:19], 2
	s_lshl_b64 s[20:21], s[20:21], 2
	s_lshl_b64 s[22:23], s[22:23], 2
	s_lshl_b64 s[24:25], s[24:25], 2
	s_lshl_b64 s[28:29], s[28:29], 2
	s_lshl_b64 s[30:31], s[30:31], 2
	s_lshl_b64 s[36:37], s[6:7], 2
	s_lshl_b64 s[38:39], s[38:39], 2
	s_lshl_b64 s[40:41], s[40:41], 2
	s_lshl_b64 s[42:43], s[42:43], 2
	s_lshl_b64 s[44:45], s[44:45], 2
	s_lshl_b64 s[46:47], s[46:47], 2
	s_lshl_b64 s[48:49], s[48:49], 2
	s_lshl_b64 s[50:51], s[50:51], 2
	s_ashr_i32 s89, s33, 31
	v_cmp_eq_u32_e64 s[6:7], 0, v136
	s_branch .LBB0_628

.LBB0_628:
	s_add_i32 s91, s84, -1
	s_add_i32 s93, s33, s86
	s_cmp_lt_i32 s84, s68
	s_cselect_b32 s56, s85, 0
	s_ashr_i32 s27, s26, 31
	s_ashr_i32 s57, s56, 31
	s_add_u32 s56, s86, s56
	s_addc_u32 s57, s87, s57
	s_lshl_b64 s[96:97], s[56:57], 2
	v_readlane_b32 s52, v245, 9
	v_readlane_b32 s54, v245, 11
	v_readlane_b32 s56, v245, 13
	v_readlane_b32 s55, v245, 12
	v_readlane_b32 s57, v245, 14
	s_add_u32 s56, s54, s96
	s_addc_u32 s57, s55, s97
	s_cmp_lt_i32 s91, s68
	v_readlane_b32 s58, v245, 15
	v_readlane_b32 s59, v245, 16
	global_load_dword v218, v187, s[56:57]
	s_cselect_b32 s56, s93, s86
	s_ashr_i32 s56, s56, 4
	s_ashr_i32 s57, s56, 31
	s_lshl_b64 s[56:57], s[56:57], 10
	v_lshl_add_u64 v[130:131], v[188:189], 0, s[56:57]
	v_lshl_add_u64 v[132:133], v[130:131], 0, s[8:9]
	v_add_co_u32_e32 v130, vcc, s69, v130
	s_mov_b64 s[56:57], s[10:11]
	s_nop 0
	v_addc_co_u32_e32 v131, vcc, 0, v131, vcc
	global_load_dwordx2 v[196:197], v[130:131], off
	global_load_dwordx2 v[194:195], v[132:133], off offset:512
	v_readlane_b32 s53, v245, 10
	v_readlane_b32 s60, v245, 17
	v_readlane_b32 s61, v245, 18
	v_readlane_b32 s62, v245, 19
	v_readlane_b32 s63, v245, 20
	v_readlane_b32 s64, v245, 21
	v_readlane_b32 s65, v245, 22
	v_readlane_b32 s66, v245, 23
	v_readlane_b32 s67, v245, 24
	s_mov_b64 s[58:59], s[0:1]
	s_waitcnt vmcnt(4)
	ds_read_b128 v[2:5], v246 offset:7168
	ds_read_b128 v[10:13], v246 offset:5120
	ds_read_b128 v[14:17], v246 offset:6144
	ds_read_b128 v[34:37], v246 offset:3072
	ds_read_b128 v[38:41], v246 offset:0
	ds_read_b128 v[42:45], v246 offset:1024
	ds_read_b128 v[46:49], v246 offset:2048
	ds_read_b128 v[70:73], v246 offset:4096
	s_waitcnt lgkmcnt(0)
	v_mul_f32_e32 v130, v222, v127
	v_fmac_f32_e32 v130, v221, v126
	v_pk_mul_f32 v[126:127], v[200:201], v[128:129]
	s_lshl_b64 s[10:11], s[26:27], 18
	v_add_f32_e32 v126, v126, v130
	v_add_f32_e32 v126, v127, v126
	s_waitcnt vmcnt(3)
	v_mul_f32_e32 v127, v123, v220
	v_fmac_f32_e32 v127, v122, v219
	v_pk_mul_f32 v[122:123], v[124:125], v[198:199]
	s_add_u32 s0, s78, s10
	v_add_f32_e32 v122, v122, v127
	v_add_f32_e32 v122, v123, v122
	v_add_f32_dpp v123, v126, v126 quad_perm:[1,0,3,2] row_mask:0xf bank_mask:0xf bound_ctrl:1
	v_mul_f32_e32 v126, v222, v111
	v_fmac_f32_e32 v126, v221, v110
	v_pk_mul_f32 v[110:111], v[200:201], v[112:113]
	v_add_f32_dpp v123, v123, v123 quad_perm:[2,3,0,1] row_mask:0xf bank_mask:0xf bound_ctrl:1
	v_add_f32_e32 v110, v110, v126
	v_add_f32_e32 v110, v111, v110
	v_mul_f32_e32 v111, v107, v220
	v_fmac_f32_e32 v111, v106, v219
	v_pk_mul_f32 v[106:107], v[108:109], v[198:199]
	v_add_f32_dpp v122, v122, v122 quad_perm:[1,0,3,2] row_mask:0xf bank_mask:0xf bound_ctrl:1
	v_add_f32_e32 v106, v106, v111
	v_add_f32_e32 v106, v107, v106
	v_add_f32_dpp v107, v110, v110 quad_perm:[1,0,3,2] row_mask:0xf bank_mask:0xf bound_ctrl:1
	v_mul_f32_e32 v110, v222, v103
	v_fmac_f32_e32 v110, v221, v102
	v_pk_mul_f32 v[102:103], v[200:201], v[104:105]
	v_add_f32_dpp v107, v107, v107 quad_perm:[2,3,0,1] row_mask:0xf bank_mask:0xf bound_ctrl:1
	v_add_f32_e32 v102, v102, v110
	v_add_f32_e32 v102, v103, v102
	v_mul_f32_e32 v103, v99, v220
	v_fmac_f32_e32 v103, v98, v219
	v_pk_mul_f32 v[98:99], v[100:101], v[198:199]
	v_add_f32_dpp v106, v106, v106 quad_perm:[1,0,3,2] row_mask:0xf bank_mask:0xf bound_ctrl:1
	v_add_f32_e32 v98, v98, v103
	v_add_f32_e32 v98, v99, v98
	v_add_f32_dpp v99, v102, v102 quad_perm:[1,0,3,2] row_mask:0xf bank_mask:0xf bound_ctrl:1
	v_mul_f32_e32 v102, v222, v95
	v_fmac_f32_e32 v102, v221, v94
	v_pk_mul_f32 v[94:95], v[200:201], v[96:97]
	v_add_f32_dpp v123, v123, v123 row_ror:4 row_mask:0xf bank_mask:0xf bound_ctrl:1
	v_add_f32_e32 v94, v94, v102
	v_add_f32_e32 v94, v95, v94
	v_mul_f32_e32 v95, v91, v220
	v_fmac_f32_e32 v95, v90, v219
	v_pk_mul_f32 v[90:91], v[92:93], v[198:199]
	v_add_f32_dpp v122, v122, v122 quad_perm:[2,3,0,1] row_mask:0xf bank_mask:0xf bound_ctrl:1
	v_add_f32_e32 v90, v90, v95
	v_add_f32_e32 v90, v91, v90
	v_add_f32_dpp v91, v94, v94 quad_perm:[1,0,3,2] row_mask:0xf bank_mask:0xf bound_ctrl:1
	v_add_f32_dpp v107, v107, v107 row_ror:4 row_mask:0xf bank_mask:0xf bound_ctrl:1
	v_add_f32_dpp v106, v106, v106 quad_perm:[2,3,0,1] row_mask:0xf bank_mask:0xf bound_ctrl:1
	v_add_f32_dpp v99, v99, v99 quad_perm:[2,3,0,1] row_mask:0xf bank_mask:0xf bound_ctrl:1
	v_add_f32_dpp v98, v98, v98 quad_perm:[1,0,3,2] row_mask:0xf bank_mask:0xf bound_ctrl:1
	v_add_f32_dpp v91, v91, v91 quad_perm:[2,3,0,1] row_mask:0xf bank_mask:0xf bound_ctrl:1
	v_add_f32_dpp v90, v90, v90 quad_perm:[1,0,3,2] row_mask:0xf bank_mask:0xf bound_ctrl:1
	v_add_f32_dpp v123, v123, v123 row_ror:8 row_mask:0xf bank_mask:0xf bound_ctrl:1
	v_add_f32_dpp v122, v122, v122 row_ror:4 row_mask:0xf bank_mask:0xf bound_ctrl:1
	v_add_f32_dpp v107, v107, v107 row_ror:8 row_mask:0xf bank_mask:0xf bound_ctrl:1
	v_add_f32_dpp v106, v106, v106 row_ror:4 row_mask:0xf bank_mask:0xf bound_ctrl:1
	v_add_f32_dpp v99, v99, v99 row_ror:4 row_mask:0xf bank_mask:0xf bound_ctrl:1
	v_add_f32_dpp v98, v98, v98 quad_perm:[2,3,0,1] row_mask:0xf bank_mask:0xf bound_ctrl:1
	v_add_f32_dpp v91, v91, v91 row_ror:4 row_mask:0xf bank_mask:0xf bound_ctrl:1
	v_add_f32_dpp v90, v90, v90 quad_perm:[2,3,0,1] row_mask:0xf bank_mask:0xf bound_ctrl:1
	v_add_f32_dpp v122, v122, v122 row_ror:8 row_mask:0xf bank_mask:0xf bound_ctrl:1
	v_mov_b32_e32 v124, v123
	v_add_f32_dpp v106, v106, v106 row_ror:8 row_mask:0xf bank_mask:0xf bound_ctrl:1
	v_mov_b32_e32 v108, v107
	v_add_f32_dpp v99, v99, v99 row_ror:8 row_mask:0xf bank_mask:0xf bound_ctrl:1
	v_add_f32_dpp v98, v98, v98 row_ror:4 row_mask:0xf bank_mask:0xf bound_ctrl:1
	v_add_f32_dpp v96, v91, v91 row_ror:8 row_mask:0xf bank_mask:0xf bound_ctrl:1
	v_add_f32_dpp v90, v90, v90 row_ror:4 row_mask:0xf bank_mask:0xf bound_ctrl:1
	v_permlane16_swap_b32_e32 v123, v124
	v_mov_b32_e32 v125, v122
	v_permlane16_swap_b32_e32 v107, v108
	v_mov_b32_e32 v109, v106
	v_add_f32_dpp v98, v98, v98 row_ror:8 row_mask:0xf bank_mask:0xf bound_ctrl:1
	v_mov_b32_e32 v100, v99
	v_add_f32_dpp v97, v90, v90 row_ror:8 row_mask:0xf bank_mask:0xf bound_ctrl:1
	v_mov_b32_e32 v102, v96
	v_permlane16_swap_b32_e32 v122, v125
	v_permlane16_swap_b32_e32 v106, v109
	v_permlane16_swap_b32_e32 v99, v100
	v_mov_b32_e32 v101, v98
	v_permlane16_swap_b32_e32 v96, v102
	v_mov_b32_e32 v103, v97
	v_max3_f32 v90, v123, s90, v107
	v_permlane16_swap_b32_e32 v98, v101
	v_permlane16_swap_b32_e32 v97, v103
	v_max3_f32 v91, v124, s90, v108
	v_max3_f32 v92, v122, s90, v106
	v_max3_f32 v155, v90, v99, v96
	v_max3_f32 v157, v91, v100, v102
	v_max3_f32 v159, v92, v98, v97
	v_sub_f32_e32 v90, 0xff800000, v155
	v_sub_f32_e32 v92, v123, v155
	v_max3_f32 v93, v125, s90, v109
	v_exp_f32_e32 v91, v90
	v_sub_f32_e32 v90, 0xff800000, v157
	v_exp_f32_e32 v164, v92
	v_sub_f32_e32 v92, v124, v157
	v_max3_f32 v165, v93, v101, v103
	v_exp_f32_e32 v93, v90
	v_sub_f32_e32 v90, 0xff800000, v159
	v_exp_f32_e32 v156, v92
	v_sub_f32_e32 v92, v122, v159
	v_exp_f32_e32 v94, v90
	v_sub_f32_e32 v90, 0xff800000, v165
	v_exp_f32_e32 v166, v92
	v_sub_f32_e32 v92, v125, v165
	v_exp_f32_e32 v95, v90
	v_exp_f32_e32 v92, v92
	v_mul_f32_e32 v154, 0, v93
	v_fma_f32 v93, 0, v93, v156
	v_mul_f32_e32 v90, 0, v95
	v_mov_b32_e32 v110, v92
	v_mul_f32_e32 v160, 0, v91
	v_mul_f32_e32 v162, 0, v94
	v_fma_f32 v104, 0, v91, v164
	v_fma_f32 v105, 0, v94, v166
	v_fmac_f32_e32 v110, 0, v95
	v_pk_fma_f32 v[94:95], v[86:87], v[92:93], v[90:91] op_sel_hi:[1,0,0]
	v_pk_fma_f32 v[90:91], v[88:89], v[92:93], v[90:91] op_sel_hi:[1,0,0]
	v_sub_f32_e32 v92, v107, v155
	v_exp_f32_e32 v168, v92
	v_sub_f32_e32 v92, v108, v157
	v_exp_f32_e32 v158, v92
	v_sub_f32_e32 v92, v106, v159
	v_exp_f32_e32 v170, v92
	v_sub_f32_e32 v92, v109, v165
	v_exp_f32_e32 v92, v92
	v_add_f32_e32 v106, v158, v93
	v_add_f32_e32 v104, v168, v104
	v_add_f32_e32 v105, v170, v105
	v_add_f32_e32 v107, v92, v110
	v_pk_fma_f32 v[90:91], v[84:85], v[92:93], v[90:91] op_sel_hi:[1,0,1]
	v_pk_fma_f32 v[92:93], v[82:83], v[92:93], v[94:95] op_sel_hi:[1,0,1]
	v_sub_f32_e32 v94, v99, v155
	v_exp_f32_e32 v172, v94
	v_sub_f32_e32 v94, v100, v157
	v_exp_f32_e32 v174, v94
	v_sub_f32_e32 v94, v98, v159
	v_exp_f32_e32 v176, v94
	v_sub_f32_e32 v94, v101, v165
	v_exp_f32_e32 v94, v94
	v_add_f32_e32 v95, v172, v104
	v_add_f32_e32 v98, v174, v106
	v_add_f32_e32 v99, v176, v105
	v_add_f32_e32 v100, v94, v107
	v_pk_fma_f32 v[92:93], v[78:79], v[94:95], v[92:93] op_sel_hi:[1,0,1]
	v_pk_fma_f32 v[90:91], v[80:81], v[94:95], v[90:91] op_sel_hi:[1,0,1]
	v_sub_f32_e32 v94, v96, v155
	v_exp_f32_e32 v206, v94
	v_sub_f32_e32 v94, v102, v157
	v_exp_f32_e32 v208, v94
	v_sub_f32_e32 v94, v97, v159
	v_exp_f32_e32 v210, v94
	v_sub_f32_e32 v94, v103, v165
	v_exp_f32_e32 v94, v94
	s_addc_u32 s1, s79, s11
	v_add_f32_e32 v167, v206, v95
	v_add_f32_e32 v169, v208, v98
	v_add_f32_e32 v171, v210, v99
	v_add_f32_e32 v173, v94, v100
	v_pk_fma_f32 v[202:203], v[76:77], v[94:95], v[90:91] op_sel_hi:[1,0,1]
	v_pk_fma_f32 v[204:205], v[74:75], v[94:95], v[92:93] op_sel_hi:[1,0,1]
	s_add_u32 s60, s58, s14
	s_addc_u32 s61, s59, s15
	global_load_dwordx4 v[182:185], v216, s[60:61] nt
	global_load_dwordx4 v[178:181], v216, s[60:61] offset:1024 nt
	s_add_u32 s60, s56, s14
	s_addc_u32 s61, s57, s15
	s_add_i32 m0, s98, 0x0
	s_nop 0
	global_load_lds_dwordx4 v216, s[60:61] nt
	global_load_dwordx4 v[90:93], v216, s[60:61] offset:1024 nt
	s_add_u32 s60, s58, s16
	s_addc_u32 s61, s59, s17
	global_load_dwordx4 v[126:129], v216, s[60:61] nt
	global_load_dwordx4 v[122:125], v216, s[60:61] offset:1024 nt
	s_add_u32 s60, s56, s16
	s_addc_u32 s61, s57, s17
	s_add_i32 m0, s98, 0x400
	s_nop 0
	global_load_lds_dwordx4 v216, s[60:61] nt
	global_load_dwordx4 v[142:145], v216, s[60:61] offset:1024 nt
	s_add_u32 s60, s58, s18
	s_addc_u32 s61, s59, s19
	global_load_dwordx4 v[110:113], v216, s[60:61] nt
	global_load_dwordx4 v[106:109], v216, s[60:61] offset:1024 nt
	s_add_u32 s60, s56, s18
	s_addc_u32 s61, s57, s19
	s_add_i32 m0, s98, 0x800
	s_nop 0
	global_load_lds_dwordx4 v216, s[60:61] nt
	global_load_dwordx4 v[146:149], v216, s[60:61] offset:1024 nt
	s_add_u32 s60, s58, s20
	s_addc_u32 s61, s59, s21
	global_load_dwordx4 v[102:105], v216, s[60:61] nt
	global_load_dwordx4 v[98:101], v216, s[60:61] offset:1024 nt
	s_add_u32 s60, s56, s20
	s_addc_u32 s61, s57, s21
	s_add_i32 m0, s98, 0xc00
	s_nop 0
	global_load_lds_dwordx4 v216, s[60:61] nt
	global_load_dwordx4 v[150:153], v216, s[60:61] offset:1024 nt
	v_pk_fma_f32 v[212:213], v[38:39], v[164:165], v[160:161] op_sel_hi:[1,0,0]
	v_pk_fma_f32 v[160:161], v[40:41], v[164:165], v[160:161] op_sel_hi:[1,0,0]
	v_pk_fma_f32 v[86:87], v[86:87], v[166:167], v[162:163] op_sel_hi:[1,0,0]
	v_pk_fma_f32 v[88:89], v[88:89], v[166:167], v[162:163] op_sel_hi:[1,0,0]
	v_pk_fma_f32 v[160:161], v[44:45], v[168:169], v[160:161] op_sel_hi:[1,0,1]
	v_pk_fma_f32 v[162:163], v[42:43], v[168:169], v[212:213] op_sel_hi:[1,0,1]
	v_pk_fma_f32 v[84:85], v[84:85], v[170:171], v[88:89] op_sel_hi:[1,0,1]
	v_pk_fma_f32 v[82:83], v[82:83], v[170:171], v[86:87] op_sel_hi:[1,0,1]
	v_pk_fma_f32 v[86:87], v[46:47], v[172:173], v[162:163] op_sel_hi:[1,0,1]
	v_pk_fma_f32 v[88:89], v[48:49], v[172:173], v[160:161] op_sel_hi:[1,0,1]
	v_pk_fma_f32 v[82:83], v[78:79], v[176:177], v[82:83] op_sel_hi:[1,0,1]
	v_pk_fma_f32 v[84:85], v[80:81], v[176:177], v[84:85] op_sel_hi:[1,0,1]
	v_pk_fma_f32 v[78:79], v[36:37], v[206:207], v[88:89] op_sel_hi:[1,0,1]
	v_pk_fma_f32 v[80:81], v[34:35], v[206:207], v[86:87] op_sel_hi:[1,0,1]
	v_pk_fma_f32 v[76:77], v[76:77], v[210:211], v[84:85] op_sel_hi:[1,0,1]
	v_pk_fma_f32 v[74:75], v[74:75], v[210:211], v[82:83] op_sel_hi:[1,0,1]
	v_mul_f32_e32 v84, v222, v119
	v_fmac_f32_e32 v84, v221, v118
	v_pk_mul_f32 v[82:83], v[200:201], v[120:121]
	v_mul_f32_e32 v85, v115, v220
	v_add_f32_e32 v82, v82, v84
	v_add_f32_e32 v84, v83, v82
	v_fmac_f32_e32 v85, v114, v219
	v_pk_mul_f32 v[82:83], v[116:117], v[198:199]
	s_add_u32 s10, s80, s10
	v_add_f32_e32 v82, v82, v85
	v_add_f32_e32 v82, v83, v82
	v_add_f32_dpp v83, v84, v84 quad_perm:[1,0,3,2] row_mask:0xf bank_mask:0xf bound_ctrl:1
	s_addc_u32 s11, s81, s11
	v_add_f32_dpp v82, v82, v82 quad_perm:[1,0,3,2] row_mask:0xf bank_mask:0xf bound_ctrl:1
	v_add_f32_dpp v83, v83, v83 quad_perm:[2,3,0,1] row_mask:0xf bank_mask:0xf bound_ctrl:1
	s_nop 0
	v_add_f32_dpp v82, v82, v82 quad_perm:[2,3,0,1] row_mask:0xf bank_mask:0xf bound_ctrl:1
	v_add_f32_dpp v83, v83, v83 row_ror:4 row_mask:0xf bank_mask:0xf bound_ctrl:1
	s_nop 0
	v_add_f32_dpp v82, v82, v82 row_ror:4 row_mask:0xf bank_mask:0xf bound_ctrl:1
	v_add_f32_dpp v83, v83, v83 row_ror:8 row_mask:0xf bank_mask:0xf bound_ctrl:1
	v_mov_b32_e32 v86, v83
	v_add_f32_dpp v85, v82, v82 row_ror:8 row_mask:0xf bank_mask:0xf bound_ctrl:1
	v_mul_f32_e32 v82, v222, v63
	v_fmac_f32_e32 v82, v221, v62
	v_pk_mul_f32 v[62:63], v[200:201], v[64:65]
	v_permlane16_swap_b32_e32 v83, v86
	v_add_f32_e32 v62, v62, v82
	v_add_f32_e32 v62, v63, v62
	v_mul_f32_e32 v63, v59, v220
	v_fmac_f32_e32 v63, v58, v219
	v_pk_mul_f32 v[58:59], v[60:61], v[198:199]
	v_mov_b32_e32 v87, v85
	v_add_f32_e32 v58, v58, v63
	v_add_f32_e32 v58, v59, v58
	v_add_f32_dpp v59, v62, v62 quad_perm:[1,0,3,2] row_mask:0xf bank_mask:0xf bound_ctrl:1
	v_mul_f32_e32 v62, v222, v55
	v_fmac_f32_e32 v62, v221, v54
	v_pk_mul_f32 v[54:55], v[200:201], v[56:57]
	v_add_f32_dpp v59, v59, v59 quad_perm:[2,3,0,1] row_mask:0xf bank_mask:0xf bound_ctrl:1
	v_add_f32_e32 v54, v54, v62
	v_add_f32_e32 v54, v55, v54
	v_mul_f32_e32 v55, v51, v220
	v_fmac_f32_e32 v55, v50, v219
	v_pk_mul_f32 v[50:51], v[52:53], v[198:199]
	v_add_f32_dpp v59, v59, v59 row_ror:4 row_mask:0xf bank_mask:0xf bound_ctrl:1
	v_add_f32_e32 v50, v50, v55
	v_add_f32_e32 v50, v51, v50
	v_add_f32_dpp v51, v54, v54 quad_perm:[1,0,3,2] row_mask:0xf bank_mask:0xf bound_ctrl:1
	v_mul_f32_e32 v54, v222, v31
	v_fmac_f32_e32 v54, v221, v30
	v_pk_mul_f32 v[30:31], v[200:201], v[32:33]
	v_add_f32_dpp v58, v58, v58 quad_perm:[1,0,3,2] row_mask:0xf bank_mask:0xf bound_ctrl:1
	v_add_f32_e32 v30, v30, v54
	v_add_f32_e32 v30, v31, v30
	v_mul_f32_e32 v31, v27, v220
	v_fmac_f32_e32 v31, v26, v219
	v_pk_mul_f32 v[26:27], v[28:29], v[198:199]
	v_add_f32_dpp v51, v51, v51 quad_perm:[2,3,0,1] row_mask:0xf bank_mask:0xf bound_ctrl:1
	v_add_f32_e32 v26, v26, v31
	v_add_f32_e32 v26, v27, v26
	v_add_f32_dpp v27, v30, v30 quad_perm:[1,0,3,2] row_mask:0xf bank_mask:0xf bound_ctrl:1
	v_add_f32_dpp v59, v59, v59 row_ror:8 row_mask:0xf bank_mask:0xf bound_ctrl:1
	v_add_f32_dpp v26, v26, v26 quad_perm:[1,0,3,2] row_mask:0xf bank_mask:0xf bound_ctrl:1
	v_add_f32_dpp v27, v27, v27 quad_perm:[2,3,0,1] row_mask:0xf bank_mask:0xf bound_ctrl:1
	v_add_f32_dpp v58, v58, v58 quad_perm:[2,3,0,1] row_mask:0xf bank_mask:0xf bound_ctrl:1
	v_add_f32_dpp v51, v51, v51 row_ror:4 row_mask:0xf bank_mask:0xf bound_ctrl:1
	v_add_f32_dpp v50, v50, v50 quad_perm:[1,0,3,2] row_mask:0xf bank_mask:0xf bound_ctrl:1
	v_add_f32_dpp v27, v27, v27 row_ror:4 row_mask:0xf bank_mask:0xf bound_ctrl:1
	v_add_f32_dpp v26, v26, v26 quad_perm:[2,3,0,1] row_mask:0xf bank_mask:0xf bound_ctrl:1
	v_add_f32_dpp v58, v58, v58 row_ror:4 row_mask:0xf bank_mask:0xf bound_ctrl:1
	v_mov_b32_e32 v60, v59
	v_add_f32_dpp v51, v51, v51 row_ror:8 row_mask:0xf bank_mask:0xf bound_ctrl:1
	v_add_f32_dpp v50, v50, v50 quad_perm:[2,3,0,1] row_mask:0xf bank_mask:0xf bound_ctrl:1
	v_add_f32_dpp v31, v27, v27 row_ror:8 row_mask:0xf bank_mask:0xf bound_ctrl:1
	v_add_f32_dpp v26, v26, v26 row_ror:4 row_mask:0xf bank_mask:0xf bound_ctrl:1
	v_add_f32_dpp v58, v58, v58 row_ror:8 row_mask:0xf bank_mask:0xf bound_ctrl:1
	v_permlane16_swap_b32_e32 v59, v60
	v_add_f32_dpp v50, v50, v50 row_ror:4 row_mask:0xf bank_mask:0xf bound_ctrl:1
	v_mov_b32_e32 v52, v51
	v_add_f32_dpp v33, v26, v26 row_ror:8 row_mask:0xf bank_mask:0xf bound_ctrl:1
	v_mov_b32_e32 v54, v31
	v_pk_fma_f32 v[26:27], v[38:39], v[156:157], v[154:155] op_sel_hi:[1,0,0]
	v_mov_b32_e32 v61, v58
	v_add_f32_dpp v50, v50, v50 row_ror:8 row_mask:0xf bank_mask:0xf bound_ctrl:1
	v_permlane16_swap_b32_e32 v51, v52
	v_permlane16_swap_b32_e32 v31, v54
	v_pk_fma_f32 v[28:29], v[40:41], v[156:157], v[154:155] op_sel_hi:[1,0,0]
	v_pk_fma_f32 v[26:27], v[42:43], v[158:159], v[26:27] op_sel_hi:[1,0,1]
	v_max3_f32 v30, v155, v83, v59
	v_permlane16_swap_b32_e32 v85, v87
	v_permlane16_swap_b32_e32 v58, v61
	v_mov_b32_e32 v53, v50
	v_mov_b32_e32 v55, v33
	v_pk_fma_f32 v[28:29], v[44:45], v[158:159], v[28:29] op_sel_hi:[1,0,1]
	v_pk_fma_f32 v[26:27], v[46:47], v[174:175], v[26:27] op_sel_hi:[1,0,1]
	v_max3_f32 v32, v157, v86, v60
	v_max3_f32 v47, v30, v51, v31
	v_permlane16_swap_b32_e32 v50, v53
	v_permlane16_swap_b32_e32 v33, v55
	v_pk_fma_f32 v[28:29], v[48:49], v[174:175], v[28:29] op_sel_hi:[1,0,1]
	v_max3_f32 v38, v159, v85, v58
	v_max3_f32 v49, v32, v52, v54
	v_pk_fma_f32 v[34:35], v[34:35], v[208:209], v[26:27] op_sel_hi:[1,0,1]
	v_sub_f32_e32 v26, v155, v47
	v_max3_f32 v39, v165, v87, v61
	v_max3_f32 v223, v38, v50, v33
	v_exp_f32_e32 v82, v26
	v_sub_f32_e32 v26, v157, v49
	v_max3_f32 v39, v39, v53, v55
	v_exp_f32_e32 v38, v26
	v_sub_f32_e32 v26, v159, v223
	v_exp_f32_e32 v84, v26
	v_sub_f32_e32 v26, v165, v39
	v_exp_f32_e32 v40, v26
	v_sub_f32_e32 v26, v83, v47
	v_exp_f32_e32 v26, v26
	v_pk_fma_f32 v[36:37], v[36:37], v[208:209], v[28:29] op_sel_hi:[1,0,1]
	v_sub_f32_e32 v28, v87, v39
	v_exp_f32_e32 v28, v28
	v_sub_f32_e32 v27, v86, v49
	v_mov_b32_e32 v29, v26
	v_exp_f32_e32 v30, v27
	v_sub_f32_e32 v27, v85, v223
	v_fmac_f32_e32 v29, v167, v82
	v_exp_f32_e32 v32, v27
	v_fma_f32 v27, v173, v40, v28
	v_pk_mul_f32 v[224:225], v[68:69], v[28:29] op_sel_hi:[1,0]
	v_pk_mul_f32 v[226:227], v[66:67], v[28:29] op_sel_hi:[1,0]
	v_sub_f32_e32 v28, v59, v47
	v_exp_f32_e32 v210, v28
	v_sub_f32_e32 v28, v60, v49
	v_exp_f32_e32 v46, v28
	v_sub_f32_e32 v28, v58, v223
	v_exp_f32_e32 v212, v28
	v_pk_mul_f32 v[86:87], v[72:73], v[26:27] op_sel_hi:[1,0]
	v_pk_mul_f32 v[88:89], v[70:71], v[26:27] op_sel_hi:[1,0]
	v_mov_b32_e32 v26, v30
	v_pk_mul_f32 v[42:43], v[72:73], v[30:31] op_sel_hi:[1,0]
	v_pk_mul_f32 v[44:45], v[70:71], v[30:31] op_sel_hi:[1,0]
	v_mov_b32_e32 v30, v32
	v_fmac_f32_e32 v30, v171, v84
	v_sub_f32_e32 v28, v61, v39
	v_exp_f32_e32 v228, v28
	v_add_f32_e32 v28, v210, v29
	v_add_f32_e32 v29, v212, v30
	v_sub_f32_e32 v30, v51, v47
	v_exp_f32_e32 v230, v30
	v_sub_f32_e32 v30, v52, v49
	v_exp_f32_e32 v48, v30
	v_sub_f32_e32 v30, v50, v223
	v_exp_f32_e32 v232, v30
	v_sub_f32_e32 v30, v53, v39
	v_exp_f32_e32 v234, v30
	v_sub_f32_e32 v30, v31, v47
	v_exp_f32_e32 v236, v30
	v_sub_f32_e32 v30, v54, v49
	v_exp_f32_e32 v238, v30
	v_sub_f32_e32 v30, v33, v223
	v_exp_f32_e32 v240, v30
	v_sub_f32_e32 v30, v55, v39
	v_exp_f32_e32 v242, v30
	v_fmac_f32_e32 v26, v169, v38
	v_add_f32_e32 v26, v46, v26
	v_add_f32_e32 v27, v228, v27
	v_add_f32_e32 v28, v230, v28
	v_add_f32_e32 v26, v48, v26
	v_add_f32_e32 v29, v232, v29
	v_add_f32_e32 v27, v234, v27
	v_add_f32_e32 v83, v236, v28
	v_add_f32_e32 v85, v238, v26
	v_add_f32_e32 v229, v240, v29
	v_add_f32_e32 v231, v242, v27
	v_pk_mul_f32 v[206:207], v[68:69], v[32:33] op_sel_hi:[1,0]
	v_pk_mul_f32 v[208:209], v[66:67], v[32:33] op_sel_hi:[1,0]
	s_add_u32 s60, s58, s22
	s_addc_u32 s61, s59, s23
	global_load_dwordx4 v[118:121], v216, s[60:61] nt
	global_load_dwordx4 v[114:117], v216, s[60:61] offset:1024 nt
	s_add_u32 s60, s56, s22
	s_addc_u32 s61, s57, s23
	s_add_i32 m0, s98, 0x1000
	s_nop 0
	global_load_lds_dwordx4 v216, s[60:61] nt
	global_load_dwordx4 v[26:29], v216, s[60:61] offset:1024 nt
	s_add_u32 s60, s58, s24
	s_addc_u32 s61, s59, s25
	global_load_dwordx4 v[70:73], v216, s[60:61] nt
	global_load_dwordx4 v[66:69], v216, s[60:61] offset:1024 nt
	s_add_u32 s60, s56, s24
	s_addc_u32 s61, s57, s25
	s_add_i32 m0, s98, 0x1400
	s_nop 0
	global_load_lds_dwordx4 v216, s[60:61] nt
	global_load_dwordx4 v[166:169], v216, s[60:61] offset:1024 nt
	s_add_u32 s60, s58, s28
	s_addc_u32 s61, s59, s29
	global_load_dwordx4 v[62:65], v216, s[60:61] nt
	global_load_dwordx4 v[58:61], v216, s[60:61] offset:1024 nt
	s_add_u32 s60, s56, s28
	s_addc_u32 s61, s57, s29
	s_add_u32 s58, s58, s30
	s_addc_u32 s59, s59, s31
	s_add_u32 s56, s56, s30
	s_addc_u32 s57, s57, s31
	s_add_i32 m0, s98, 0x1800
	s_nop 0
	global_load_lds_dwordx4 v216, s[60:61] nt
	global_load_dwordx4 v[158:161], v216, s[60:61] offset:1024 nt
	global_load_dwordx4 v[54:57], v216, s[58:59] nt
	global_load_dwordx4 v[50:53], v216, s[58:59] offset:1024 nt
	s_add_i32 m0, s98, 0x1c00
	s_nop 0
	global_load_lds_dwordx4 v216, s[56:57] nt
	global_load_dwordx4 v[154:157], v216, s[56:57] offset:1024 nt
	v_pk_fma_f32 v[80:81], v[80:81], v[82:83], v[88:89] op_sel_hi:[1,0,1]
	v_pk_fma_f32 v[78:79], v[78:79], v[82:83], v[86:87] op_sel_hi:[1,0,1]
	v_pk_fma_f32 v[74:75], v[74:75], v[84:85], v[208:209] op_sel_hi:[1,0,1]
	v_pk_fma_f32 v[76:77], v[76:77], v[84:85], v[206:207] op_sel_hi:[1,0,1]
	v_pk_fma_f32 v[78:79], v[12:13], v[210:211], v[78:79] op_sel_hi:[1,0,1]
	v_pk_fma_f32 v[80:81], v[10:11], v[210:211], v[80:81] op_sel_hi:[1,0,1]
	v_pk_fma_f32 v[76:77], v[20:21], v[212:213], v[76:77] op_sel_hi:[1,0,1]
	v_pk_fma_f32 v[74:75], v[18:19], v[212:213], v[74:75] op_sel_hi:[1,0,1]
	v_pk_fma_f32 v[80:81], v[14:15], v[230:231], v[80:81] op_sel_hi:[1,0,1]
	v_pk_fma_f32 v[78:79], v[16:17], v[230:231], v[78:79] op_sel_hi:[1,0,1]
	v_pk_fma_f32 v[74:75], v[22:23], v[232:233], v[74:75] op_sel_hi:[1,0,1]
	v_pk_fma_f32 v[76:77], v[24:25], v[232:233], v[76:77] op_sel_hi:[1,0,1]
	v_pk_fma_f32 v[206:207], v[4:5], v[236:237], v[78:79] op_sel_hi:[1,0,1]
	v_pk_fma_f32 v[208:209], v[2:3], v[236:237], v[80:81] op_sel_hi:[1,0,1]
	v_pk_fma_f32 v[210:211], v[8:9], v[240:241], v[76:77] op_sel_hi:[1,0,1]
	v_pk_fma_f32 v[212:213], v[6:7], v[240:241], v[74:75] op_sel_hi:[1,0,1]
	s_waitcnt vmcnt(31)
	v_mul_f32_e32 v41, v222, v183
	v_fmac_f32_e32 v41, v221, v182
	v_pk_mul_f32 v[74:75], v[184:185], v[200:201]
	s_waitcnt vmcnt(30)
	v_mul_f32_e32 v76, v220, v179
	v_add_f32_e32 v41, v74, v41
	v_add_f32_e32 v41, v75, v41
	v_fmac_f32_e32 v76, v219, v178
	v_pk_mul_f32 v[74:75], v[180:181], v[198:199]
	v_add_f32_dpp v41, v41, v41 quad_perm:[1,0,3,2] row_mask:0xf bank_mask:0xf bound_ctrl:1
	v_add_f32_e32 v74, v74, v76
	v_add_f32_e32 v74, v75, v74
	v_add_f32_dpp v41, v41, v41 quad_perm:[2,3,0,1] row_mask:0xf bank_mask:0xf bound_ctrl:1
	s_waitcnt vmcnt(26)
	v_mul_f32_e32 v80, v220, v123
	v_fmac_f32_e32 v80, v219, v122
	v_add_f32_dpp v41, v41, v41 row_ror:4 row_mask:0xf bank_mask:0xf bound_ctrl:1
	s_waitcnt vmcnt(22)
	v_mul_f32_e32 v86, v220, v107
	v_fmac_f32_e32 v86, v219, v106
	v_add_f32_dpp v76, v41, v41 row_ror:8 row_mask:0xf bank_mask:0xf bound_ctrl:1
	v_add_f32_dpp v41, v74, v74 quad_perm:[1,0,3,2] row_mask:0xf bank_mask:0xf bound_ctrl:1
	v_pk_mul_f32 v[74:75], v[128:129], v[200:201]
	s_waitcnt vmcnt(18)
	v_mul_f32_e32 v99, v220, v99
	v_add_f32_dpp v41, v41, v41 quad_perm:[2,3,0,1] row_mask:0xf bank_mask:0xf bound_ctrl:1
	v_fmac_f32_e32 v99, v219, v98
	v_mov_b32_e32 v78, v76
	v_add_f32_dpp v41, v41, v41 row_ror:4 row_mask:0xf bank_mask:0xf bound_ctrl:1
	s_nop 0
	v_permlane16_swap_b32_e32 v76, v78
	v_add_f32_dpp v77, v41, v41 row_ror:8 row_mask:0xf bank_mask:0xf bound_ctrl:1
	v_mul_f32_e32 v41, v222, v127
	v_fmac_f32_e32 v41, v221, v126
	v_add_f32_e32 v41, v74, v41
	v_add_f32_e32 v41, v75, v41
	v_pk_mul_f32 v[74:75], v[124:125], v[198:199]
	v_mov_b32_e32 v79, v77
	v_add_f32_dpp v41, v41, v41 quad_perm:[1,0,3,2] row_mask:0xf bank_mask:0xf bound_ctrl:1
	v_add_f32_e32 v74, v74, v80
	v_add_f32_e32 v74, v75, v74
	v_add_f32_dpp v41, v41, v41 quad_perm:[2,3,0,1] row_mask:0xf bank_mask:0xf bound_ctrl:1
	v_permlane16_swap_b32_e32 v77, v79
	s_nop 0
	v_add_f32_dpp v41, v41, v41 row_ror:4 row_mask:0xf bank_mask:0xf bound_ctrl:1
	s_nop 1
	v_add_f32_dpp v80, v41, v41 row_ror:8 row_mask:0xf bank_mask:0xf bound_ctrl:1
	v_add_f32_dpp v41, v74, v74 quad_perm:[1,0,3,2] row_mask:0xf bank_mask:0xf bound_ctrl:1
	v_pk_mul_f32 v[74:75], v[112:113], v[200:201]
	v_mov_b32_e32 v82, v80
	v_add_f32_dpp v41, v41, v41 quad_perm:[2,3,0,1] row_mask:0xf bank_mask:0xf bound_ctrl:1
	s_nop 0
	v_permlane16_swap_b32_e32 v80, v82
	v_add_f32_dpp v41, v41, v41 row_ror:4 row_mask:0xf bank_mask:0xf bound_ctrl:1
	s_nop 1
	v_add_f32_dpp v81, v41, v41 row_ror:8 row_mask:0xf bank_mask:0xf bound_ctrl:1
	v_mul_f32_e32 v41, v222, v111
	v_fmac_f32_e32 v41, v221, v110
	v_add_f32_e32 v41, v74, v41
	v_add_f32_e32 v41, v75, v41
	v_pk_mul_f32 v[74:75], v[108:109], v[198:199]
	v_mov_b32_e32 v84, v81
	v_add_f32_dpp v41, v41, v41 quad_perm:[1,0,3,2] row_mask:0xf bank_mask:0xf bound_ctrl:1
	v_add_f32_e32 v74, v74, v86
	v_add_f32_e32 v74, v75, v74
	v_add_f32_dpp v41, v41, v41 quad_perm:[2,3,0,1] row_mask:0xf bank_mask:0xf bound_ctrl:1
	v_permlane16_swap_b32_e32 v81, v84
	s_nop 0
	v_add_f32_dpp v41, v41, v41 row_ror:4 row_mask:0xf bank_mask:0xf bound_ctrl:1
	s_nop 1
	v_add_f32_dpp v86, v41, v41 row_ror:8 row_mask:0xf bank_mask:0xf bound_ctrl:1
	v_add_f32_dpp v41, v74, v74 quad_perm:[1,0,3,2] row_mask:0xf bank_mask:0xf bound_ctrl:1
	v_pk_mul_f32 v[74:75], v[104:105], v[200:201]
	v_mov_b32_e32 v88, v86
	v_add_f32_dpp v41, v41, v41 quad_perm:[2,3,0,1] row_mask:0xf bank_mask:0xf bound_ctrl:1
	s_nop 0
	v_permlane16_swap_b32_e32 v86, v88
	v_add_f32_dpp v41, v41, v41 row_ror:4 row_mask:0xf bank_mask:0xf bound_ctrl:1
	s_nop 1
	v_add_f32_dpp v87, v41, v41 row_ror:8 row_mask:0xf bank_mask:0xf bound_ctrl:1
	v_mul_f32_e32 v41, v222, v103
	v_fmac_f32_e32 v41, v221, v102
	v_add_f32_e32 v41, v74, v41
	v_add_f32_e32 v41, v75, v41
	v_pk_mul_f32 v[74:75], v[100:101], v[198:199]
	v_mov_b32_e32 v89, v87
	v_add_f32_dpp v41, v41, v41 quad_perm:[1,0,3,2] row_mask:0xf bank_mask:0xf bound_ctrl:1
	v_add_f32_e32 v74, v74, v99
	v_add_f32_e32 v74, v75, v74
	v_add_f32_dpp v41, v41, v41 quad_perm:[2,3,0,1] row_mask:0xf bank_mask:0xf bound_ctrl:1
	v_permlane16_swap_b32_e32 v87, v89
	s_nop 0
	v_add_f32_dpp v41, v41, v41 row_ror:4 row_mask:0xf bank_mask:0xf bound_ctrl:1
	s_nop 1
	v_add_f32_dpp v98, v41, v41 row_ror:8 row_mask:0xf bank_mask:0xf bound_ctrl:1
	v_add_f32_dpp v41, v74, v74 quad_perm:[1,0,3,2] row_mask:0xf bank_mask:0xf bound_ctrl:1
	v_mov_b32_e32 v100, v98
	s_nop 1
	v_permlane16_swap_b32_e32 v98, v100
	v_add_f32_dpp v41, v41, v41 quad_perm:[2,3,0,1] row_mask:0xf bank_mask:0xf bound_ctrl:1
	s_nop 1
	v_add_f32_dpp v41, v41, v41 row_ror:4 row_mask:0xf bank_mask:0xf bound_ctrl:1
	v_pk_fma_f32 v[74:75], v[204:205], v[40:41], v[226:227] op_sel_hi:[1,0,1]
	s_nop 0
	v_pk_fma_f32 v[18:19], v[18:19], v[228:229], v[74:75] op_sel_hi:[1,0,1]
	v_add_f32_dpp v99, v41, v41 row_ror:8 row_mask:0xf bank_mask:0xf bound_ctrl:1
	v_pk_fma_f32 v[40:41], v[202:203], v[40:41], v[224:225] op_sel_hi:[1,0,1]
	v_pk_fma_f32 v[18:19], v[22:23], v[234:235], v[18:19] op_sel_hi:[1,0,1]
	v_pk_fma_f32 v[20:21], v[20:21], v[228:229], v[40:41] op_sel_hi:[1,0,1]
	v_pk_fma_f32 v[6:7], v[6:7], v[242:243], v[18:19] op_sel_hi:[1,0,1]
	v_max3_f32 v18, v47, v76, v80
	v_max3_f32 v19, v49, v78, v82
	v_mov_b32_e32 v101, v99
	v_pk_fma_f32 v[20:21], v[24:25], v[234:235], v[20:21] op_sel_hi:[1,0,1]
	v_max3_f32 v225, v18, v86, v98
	v_max3_f32 v227, v19, v88, v100
	v_pk_fma_f32 v[18:19], v[34:35], v[38:39], v[44:45] op_sel_hi:[1,0,1]
	v_permlane16_swap_b32_e32 v99, v101
	v_pk_fma_f32 v[8:9], v[8:9], v[242:243], v[20:21] op_sel_hi:[1,0,1]
	v_max3_f32 v20, v223, v77, v81
	v_max3_f32 v21, v39, v79, v84
	v_pk_fma_f32 v[10:11], v[10:11], v[46:47], v[18:19] op_sel_hi:[1,0,1]
	v_max3_f32 v233, v20, v87, v99
	v_max3_f32 v235, v21, v89, v101
	v_pk_fma_f32 v[20:21], v[36:37], v[38:39], v[42:43] op_sel_hi:[1,0,1]
	v_pk_fma_f32 v[10:11], v[14:15], v[48:49], v[10:11] op_sel_hi:[1,0,1]
	v_pk_fma_f32 v[12:13], v[12:13], v[46:47], v[20:21] op_sel_hi:[1,0,1]
	v_pk_fma_f32 v[2:3], v[2:3], v[238:239], v[10:11] op_sel_hi:[1,0,1]
	v_sub_f32_e32 v11, v223, v233
	v_pk_fma_f32 v[12:13], v[16:17], v[48:49], v[12:13] op_sel_hi:[1,0,1]
	v_exp_f32_e32 v24, v11
	v_sub_f32_e32 v11, v39, v235
	v_pk_fma_f32 v[4:5], v[4:5], v[238:239], v[12:13] op_sel_hi:[1,0,1]
	v_exp_f32_e32 v12, v11
	v_sub_f32_e32 v11, v76, v225
	v_exp_f32_e32 v14, v11
	v_sub_f32_e32 v11, v78, v227
	v_exp_f32_e32 v16, v11
	v_sub_f32_e32 v11, v77, v233
	v_sub_f32_e32 v10, v47, v225
	v_exp_f32_e32 v20, v11
	v_exp_f32_e32 v22, v10
	v_sub_f32_e32 v10, v49, v227
	v_exp_f32_e32 v10, v10
	v_sub_f32_e32 v13, v79, v235
	v_exp_f32_e32 v18, v13
	v_mov_b32_e32 v21, v20
	v_mov_b32_e32 v19, v16
	v_fmac_f32_e32 v21, v229, v24
	v_sub_f32_e32 v23, v87, v233
	v_fmac_f32_e32 v19, v85, v10
	v_pk_mul_f32 v[182:183], v[92:93], v[20:21] op_sel_hi:[1,0]
	v_pk_mul_f32 v[184:185], v[90:91], v[20:21] op_sel_hi:[1,0]
	v_sub_f32_e32 v20, v81, v233
	v_exp_f32_e32 v232, v23
	v_sub_f32_e32 v23, v89, v235
	v_fma_f32 v11, v231, v12, v18
	v_pk_mul_f32 v[202:203], v[92:93], v[18:19] op_sel_hi:[1,0]
	v_pk_mul_f32 v[204:205], v[90:91], v[18:19] op_sel_hi:[1,0]
	v_sub_f32_e32 v18, v80, v225
	v_exp_f32_e32 v226, v20
	v_sub_f32_e32 v20, v84, v235
	v_exp_f32_e32 v234, v23
	v_sub_f32_e32 v23, v98, v225
	v_exp_f32_e32 v224, v18
	v_sub_f32_e32 v18, v82, v227
	v_exp_f32_e32 v228, v20
	v_sub_f32_e32 v20, v86, v225
	v_exp_f32_e32 v236, v23
	v_sub_f32_e32 v23, v100, v227
	v_exp_f32_e32 v18, v18
	v_exp_f32_e32 v230, v20
	v_sub_f32_e32 v20, v88, v227
	v_exp_f32_e32 v238, v23
	v_sub_f32_e32 v23, v99, v233
	v_exp_f32_e32 v20, v20
	v_exp_f32_e32 v240, v23
	v_sub_f32_e32 v23, v101, v235
	v_mov_b32_e32 v13, v14
	v_exp_f32_e32 v242, v23
	v_fmac_f32_e32 v13, v83, v22
	v_add_f32_e32 v13, v224, v13
	v_add_f32_e32 v19, v18, v19
	v_add_f32_e32 v21, v226, v21
	v_add_f32_e32 v11, v228, v11
	v_add_f32_e32 v13, v230, v13
	v_add_f32_e32 v19, v20, v19
	v_add_f32_e32 v21, v232, v21
	v_add_f32_e32 v11, v234, v11
	s_waitcnt vmcnt(17)
	ds_read_b128 v[94:97], v246 offset:0
	ds_read_b128 v[130:133], v246 offset:1024
	ds_read_b128 v[134:137], v246 offset:2048
	ds_read_b128 v[138:141], v246 offset:3072
	s_waitcnt lgkmcnt(0)
	v_pk_mul_f32 v[178:179], v[96:97], v[14:15] op_sel_hi:[1,0]
	v_pk_mul_f32 v[180:181], v[94:95], v[14:15] op_sel_hi:[1,0]
	v_pk_mul_f32 v[14:15], v[96:97], v[16:17] op_sel_hi:[1,0]
	v_pk_mul_f32 v[16:17], v[94:95], v[16:17] op_sel_hi:[1,0]
	v_add_f32_e32 v13, v236, v13
	v_add_f32_e32 v19, v238, v19
	v_add_f32_e32 v21, v240, v21
	v_add_f32_e32 v11, v242, v11
	s_add_u32 s56, s0, s36
	s_addc_u32 s57, s1, s37
	global_load_dwordx4 v[126:129], v216, s[56:57] nt
	global_load_dwordx4 v[122:125], v216, s[56:57] offset:1024 nt
	s_add_u32 s56, s10, s36
	s_addc_u32 s57, s11, s37
	s_add_i32 m0, s98, 0x0
	s_nop 0
	global_load_lds_dwordx4 v216, s[56:57] nt
	global_load_dwordx4 v[86:89], v216, s[56:57] offset:1024 nt
	s_add_u32 s56, s0, s38
	s_addc_u32 s57, s1, s39
	global_load_dwordx4 v[110:113], v216, s[56:57] nt
	global_load_dwordx4 v[106:109], v216, s[56:57] offset:1024 nt
	s_add_u32 s56, s10, s38
	s_addc_u32 s57, s11, s39
	s_add_i32 m0, s98, 0x400
	s_nop 0
	global_load_lds_dwordx4 v216, s[56:57] nt
	global_load_dwordx4 v[82:85], v216, s[56:57] offset:1024 nt
	s_add_u32 s56, s0, s40
	s_addc_u32 s57, s1, s41
	global_load_dwordx4 v[102:105], v216, s[56:57] nt
	global_load_dwordx4 v[98:101], v216, s[56:57] offset:1024 nt
	s_add_u32 s56, s10, s40
	s_addc_u32 s57, s11, s41
	s_add_i32 m0, s98, 0x800
	s_nop 0
	global_load_lds_dwordx4 v216, s[56:57] nt
	global_load_dwordx4 v[78:81], v216, s[56:57] offset:1024 nt
	s_add_u32 s56, s0, s42
	s_addc_u32 s57, s1, s43
	global_load_dwordx4 v[94:97], v216, s[56:57] nt
	global_load_dwordx4 v[90:93], v216, s[56:57] offset:1024 nt
	s_add_u32 s56, s10, s42
	s_addc_u32 s57, s11, s43
	s_add_i32 m0, s98, 0xc00
	s_nop 0
	global_load_lds_dwordx4 v216, s[56:57] nt
	global_load_dwordx4 v[74:77], v216, s[56:57] offset:1024 nt
	v_pk_fma_f32 v[180:181], v[208:209], v[22:23], v[180:181] op_sel_hi:[1,0,1]
	v_pk_fma_f32 v[22:23], v[206:207], v[22:23], v[178:179] op_sel_hi:[1,0,1]
	v_pk_fma_f32 v[178:179], v[212:213], v[24:25], v[184:185] op_sel_hi:[1,0,1]
	v_pk_fma_f32 v[24:25], v[210:211], v[24:25], v[182:183] op_sel_hi:[1,0,1]
	v_pk_fma_f32 v[22:23], v[132:133], v[224:225], v[22:23] op_sel_hi:[1,0,1]
	v_pk_fma_f32 v[180:181], v[130:131], v[224:225], v[180:181] op_sel_hi:[1,0,1]
	v_pk_fma_f32 v[24:25], v[144:145], v[226:227], v[24:25] op_sel_hi:[1,0,1]
	v_pk_fma_f32 v[178:179], v[142:143], v[226:227], v[178:179] op_sel_hi:[1,0,1]
	v_pk_fma_f32 v[182:183], v[134:135], v[230:231], v[180:181] op_sel_hi:[1,0,1]
	v_pk_fma_f32 v[22:23], v[136:137], v[230:231], v[22:23] op_sel_hi:[1,0,1]
	v_pk_fma_f32 v[206:207], v[146:147], v[232:233], v[178:179] op_sel_hi:[1,0,1]
	v_pk_fma_f32 v[24:25], v[148:149], v[232:233], v[24:25] op_sel_hi:[1,0,1]
	s_waitcnt vmcnt(33)
	v_pk_fma_f32 v[180:181], v[140:141], v[236:237], v[22:23] op_sel_hi:[1,0,1]
	v_pk_fma_f32 v[184:185], v[138:139], v[236:237], v[182:183] op_sel_hi:[1,0,1]
	s_waitcnt vmcnt(32)
	v_pk_fma_f32 v[178:179], v[152:153], v[240:241], v[24:25] op_sel_hi:[1,0,1]
	v_pk_fma_f32 v[182:183], v[150:151], v[240:241], v[206:207] op_sel_hi:[1,0,1]
	s_waitcnt vmcnt(31)
	v_mul_f32_e32 v24, v222, v119
	v_fmac_f32_e32 v24, v221, v118
	v_pk_mul_f32 v[22:23], v[120:121], v[200:201]
	s_waitcnt vmcnt(30)
	v_mul_f32_e32 v25, v220, v115
	v_add_f32_e32 v22, v22, v24
	v_add_f32_e32 v24, v23, v22
	v_fmac_f32_e32 v25, v219, v114
	v_pk_mul_f32 v[22:23], v[116:117], v[198:199]
	s_waitcnt vmcnt(27)
	v_mul_f32_e32 v71, v222, v71
	v_add_f32_e32 v22, v22, v25
	v_add_f32_e32 v22, v23, v22
	v_add_f32_dpp v23, v24, v24 quad_perm:[1,0,3,2] row_mask:0xf bank_mask:0xf bound_ctrl:1
	v_fmac_f32_e32 v71, v221, v70
	v_add_f32_dpp v22, v22, v22 quad_perm:[1,0,3,2] row_mask:0xf bank_mask:0xf bound_ctrl:1
	v_add_f32_dpp v23, v23, v23 quad_perm:[2,3,0,1] row_mask:0xf bank_mask:0xf bound_ctrl:1
	s_waitcnt vmcnt(26)
	v_mul_f32_e32 v67, v220, v67
	v_add_f32_dpp v22, v22, v22 quad_perm:[2,3,0,1] row_mask:0xf bank_mask:0xf bound_ctrl:1
	v_add_f32_dpp v23, v23, v23 row_ror:4 row_mask:0xf bank_mask:0xf bound_ctrl:1
	v_fmac_f32_e32 v67, v219, v66
	v_add_f32_dpp v22, v22, v22 row_ror:4 row_mask:0xf bank_mask:0xf bound_ctrl:1
	v_add_f32_dpp v24, v23, v23 row_ror:8 row_mask:0xf bank_mask:0xf bound_ctrl:1
	s_waitcnt vmcnt(23)
	v_mul_f32_e32 v63, v222, v63
	v_add_f32_dpp v25, v22, v22 row_ror:8 row_mask:0xf bank_mask:0xf bound_ctrl:1
	v_pk_mul_f32 v[22:23], v[72:73], v[200:201]
	v_fmac_f32_e32 v63, v221, v62
	v_add_f32_e32 v22, v22, v71
	v_add_f32_e32 v70, v23, v22
	v_pk_mul_f32 v[22:23], v[68:69], v[198:199]
	s_waitcnt vmcnt(22)
	v_mul_f32_e32 v59, v220, v59
	v_add_f32_e32 v22, v22, v67
	v_add_f32_e32 v22, v23, v22
	v_add_f32_dpp v23, v70, v70 quad_perm:[1,0,3,2] row_mask:0xf bank_mask:0xf bound_ctrl:1
	v_fmac_f32_e32 v59, v219, v58
	v_add_f32_dpp v22, v22, v22 quad_perm:[1,0,3,2] row_mask:0xf bank_mask:0xf bound_ctrl:1
	v_add_f32_dpp v23, v23, v23 quad_perm:[2,3,0,1] row_mask:0xf bank_mask:0xf bound_ctrl:1
	s_waitcnt vmcnt(19)
	v_mul_f32_e32 v55, v222, v55
	v_add_f32_dpp v22, v22, v22 quad_perm:[2,3,0,1] row_mask:0xf bank_mask:0xf bound_ctrl:1
	v_add_f32_dpp v23, v23, v23 row_ror:4 row_mask:0xf bank_mask:0xf bound_ctrl:1
	v_fmac_f32_e32 v55, v221, v54
	v_add_f32_dpp v22, v22, v22 row_ror:4 row_mask:0xf bank_mask:0xf bound_ctrl:1
	v_add_f32_dpp v66, v23, v23 row_ror:8 row_mask:0xf bank_mask:0xf bound_ctrl:1
	s_waitcnt vmcnt(18)
	v_mul_f32_e32 v51, v220, v51
	v_add_f32_dpp v67, v22, v22 row_ror:8 row_mask:0xf bank_mask:0xf bound_ctrl:1
	v_pk_mul_f32 v[22:23], v[64:65], v[200:201]
	v_fmac_f32_e32 v51, v219, v50
	v_add_f32_e32 v22, v22, v63
	v_add_f32_e32 v62, v23, v22
	v_pk_mul_f32 v[22:23], v[60:61], v[198:199]
	v_pk_fma_f32 v[6:7], v[6:7], v[12:13], v[204:205] op_sel_hi:[1,0,1]
	v_add_f32_e32 v22, v22, v59
	v_add_f32_e32 v22, v23, v22
	v_add_f32_dpp v23, v62, v62 quad_perm:[1,0,3,2] row_mask:0xf bank_mask:0xf bound_ctrl:1
	v_mov_b32_e32 v114, v24
	v_add_f32_dpp v22, v22, v22 quad_perm:[1,0,3,2] row_mask:0xf bank_mask:0xf bound_ctrl:1
	v_add_f32_dpp v23, v23, v23 quad_perm:[2,3,0,1] row_mask:0xf bank_mask:0xf bound_ctrl:1
	v_mov_b32_e32 v68, v66
	v_add_f32_dpp v22, v22, v22 quad_perm:[2,3,0,1] row_mask:0xf bank_mask:0xf bound_ctrl:1
	v_add_f32_dpp v23, v23, v23 row_ror:4 row_mask:0xf bank_mask:0xf bound_ctrl:1
	v_pk_fma_f32 v[8:9], v[8:9], v[12:13], v[202:203] op_sel_hi:[1,0,1]
	v_add_f32_dpp v22, v22, v22 row_ror:4 row_mask:0xf bank_mask:0xf bound_ctrl:1
	v_add_f32_dpp v58, v23, v23 row_ror:8 row_mask:0xf bank_mask:0xf bound_ctrl:1
	v_pk_fma_f32 v[6:7], v[142:143], v[228:229], v[6:7] op_sel_hi:[1,0,1]
	v_add_f32_dpp v59, v22, v22 row_ror:8 row_mask:0xf bank_mask:0xf bound_ctrl:1
	v_pk_mul_f32 v[22:23], v[56:57], v[200:201]
	v_permlane16_swap_b32_e32 v24, v114
	v_add_f32_e32 v22, v22, v55
	v_add_f32_e32 v54, v23, v22
	v_pk_mul_f32 v[22:23], v[52:53], v[198:199]
	v_permlane16_swap_b32_e32 v66, v68
	v_add_f32_e32 v22, v22, v51
	v_add_f32_e32 v22, v23, v22
	v_add_f32_dpp v23, v54, v54 quad_perm:[1,0,3,2] row_mask:0xf bank_mask:0xf bound_ctrl:1
	v_mov_b32_e32 v60, v58
	v_add_f32_dpp v22, v22, v22 quad_perm:[1,0,3,2] row_mask:0xf bank_mask:0xf bound_ctrl:1
	v_add_f32_dpp v23, v23, v23 quad_perm:[2,3,0,1] row_mask:0xf bank_mask:0xf bound_ctrl:1
	v_pk_fma_f32 v[8:9], v[144:145], v[228:229], v[8:9] op_sel_hi:[1,0,1]
	v_add_f32_dpp v22, v22, v22 quad_perm:[2,3,0,1] row_mask:0xf bank_mask:0xf bound_ctrl:1
	v_add_f32_dpp v23, v23, v23 row_ror:4 row_mask:0xf bank_mask:0xf bound_ctrl:1
	v_pk_fma_f32 v[6:7], v[146:147], v[234:235], v[6:7] op_sel_hi:[1,0,1]
	v_add_f32_dpp v22, v22, v22 row_ror:4 row_mask:0xf bank_mask:0xf bound_ctrl:1
	v_add_f32_dpp v23, v23, v23 row_ror:8 row_mask:0xf bank_mask:0xf bound_ctrl:1
	v_mov_b32_e32 v50, v23
	v_pk_fma_f32 v[2:3], v[2:3], v[10:11], v[16:17] op_sel_hi:[1,0,1]
	v_mov_b32_e32 v115, v25
	v_mov_b32_e32 v69, v67
	v_permlane16_swap_b32_e32 v58, v60
	v_add_f32_dpp v22, v22, v22 row_ror:8 row_mask:0xf bank_mask:0xf bound_ctrl:1
	v_permlane16_swap_b32_e32 v23, v50
	v_pk_fma_f32 v[8:9], v[148:149], v[234:235], v[8:9] op_sel_hi:[1,0,1]
	v_pk_fma_f32 v[148:149], v[150:151], v[242:243], v[6:7] op_sel_hi:[1,0,1]
	v_max3_f32 v6, v225, v24, v66
	v_pk_fma_f32 v[4:5], v[4:5], v[10:11], v[14:15] op_sel_hi:[1,0,1]
	v_pk_fma_f32 v[2:3], v[130:131], v[18:19], v[2:3] op_sel_hi:[1,0,1]
	v_permlane16_swap_b32_e32 v25, v115
	v_permlane16_swap_b32_e32 v67, v69
	v_mov_b32_e32 v61, v59
	v_mov_b32_e32 v51, v22
	v_max3_f32 v7, v227, v114, v68
	v_max3_f32 v142, v6, v58, v23
	v_pk_fma_f32 v[4:5], v[132:133], v[18:19], v[4:5] op_sel_hi:[1,0,1]
	v_pk_fma_f32 v[2:3], v[134:135], v[20:21], v[2:3] op_sel_hi:[1,0,1]
	v_permlane16_swap_b32_e32 v59, v61
	v_permlane16_swap_b32_e32 v22, v51
	v_pk_fma_f32 v[146:147], v[152:153], v[242:243], v[8:9] op_sel_hi:[1,0,1]
	v_max3_f32 v8, v233, v25, v67
	v_max3_f32 v144, v7, v60, v50
	v_pk_fma_f32 v[4:5], v[136:137], v[20:21], v[4:5] op_sel_hi:[1,0,1]
	v_pk_fma_f32 v[136:137], v[138:139], v[238:239], v[2:3] op_sel_hi:[1,0,1]
	v_sub_f32_e32 v2, v225, v142
	v_max3_f32 v9, v235, v115, v69
	v_max3_f32 v143, v8, v59, v22
	v_exp_f32_e32 v138, v2
	v_sub_f32_e32 v2, v227, v144
	v_max3_f32 v145, v9, v61, v51
	v_pk_fma_f32 v[134:135], v[140:141], v[238:239], v[4:5] op_sel_hi:[1,0,1]
	v_exp_f32_e32 v140, v2
	v_sub_f32_e32 v2, v233, v143
	v_exp_f32_e32 v150, v2
	v_sub_f32_e32 v2, v235, v145
	v_exp_f32_e32 v152, v2
	v_sub_f32_e32 v2, v24, v142
	v_exp_f32_e32 v2, v2
	v_sub_f32_e32 v4, v115, v145
	v_exp_f32_e32 v4, v4
	v_sub_f32_e32 v3, v114, v144
	v_mov_b32_e32 v5, v2
	v_exp_f32_e32 v6, v3
	v_sub_f32_e32 v3, v25, v143
	v_fmac_f32_e32 v5, v13, v138
	v_exp_f32_e32 v8, v3
	v_fma_f32 v3, v11, v152, v4
	v_pk_mul_f32 v[210:211], v[28:29], v[4:5] op_sel_hi:[1,0]
	v_pk_mul_f32 v[212:213], v[26:27], v[4:5] op_sel_hi:[1,0]
	v_sub_f32_e32 v4, v66, v142
	v_exp_f32_e32 v220, v4
	v_sub_f32_e32 v4, v68, v144
	v_exp_f32_e32 v222, v4
	v_sub_f32_e32 v4, v67, v143
	v_exp_f32_e32 v224, v4
	s_waitcnt vmcnt(17)
	ds_read_b128 v[30:33], v246 offset:4096
	ds_read_b128 v[174:177], v246 offset:5120
	ds_read_b128 v[170:173], v246 offset:6144
	ds_read_b128 v[162:165], v246 offset:7168
	s_waitcnt lgkmcnt(0)
	v_pk_mul_f32 v[198:199], v[32:33], v[2:3] op_sel_hi:[1,0]
	v_pk_mul_f32 v[200:201], v[30:31], v[2:3] op_sel_hi:[1,0]
	v_mov_b32_e32 v2, v6
	v_pk_mul_f32 v[202:203], v[32:33], v[6:7] op_sel_hi:[1,0]
	v_pk_mul_f32 v[204:205], v[30:31], v[6:7] op_sel_hi:[1,0]
	v_mov_b32_e32 v6, v8
	v_fmac_f32_e32 v6, v21, v150
	v_sub_f32_e32 v4, v69, v145
	v_exp_f32_e32 v226, v4
	v_add_f32_e32 v4, v220, v5
	v_add_f32_e32 v5, v224, v6
	v_sub_f32_e32 v6, v58, v142
	v_exp_f32_e32 v228, v6
	v_sub_f32_e32 v6, v60, v144
	v_exp_f32_e32 v230, v6
	v_sub_f32_e32 v6, v59, v143
	v_exp_f32_e32 v232, v6
	v_sub_f32_e32 v6, v61, v145
	v_exp_f32_e32 v234, v6
	v_sub_f32_e32 v6, v23, v142
	v_exp_f32_e32 v236, v6
	v_sub_f32_e32 v6, v50, v144
	v_exp_f32_e32 v238, v6
	v_sub_f32_e32 v6, v22, v143
	v_exp_f32_e32 v240, v6
	v_sub_f32_e32 v6, v51, v145
	v_exp_f32_e32 v242, v6
	v_fmac_f32_e32 v2, v19, v140
	v_add_f32_e32 v2, v222, v2
	v_add_f32_e32 v3, v226, v3
	v_add_f32_e32 v4, v228, v4
	v_add_f32_e32 v2, v230, v2
	v_add_f32_e32 v5, v232, v5
	v_add_f32_e32 v3, v234, v3
	v_add_f32_e32 v130, v236, v4
	v_add_f32_e32 v132, v238, v2
	v_add_f32_e32 v131, v240, v5
	v_add_f32_e32 v133, v242, v3
	v_pk_mul_f32 v[206:207], v[28:29], v[8:9] op_sel_hi:[1,0]
	v_pk_mul_f32 v[208:209], v[26:27], v[8:9] op_sel_hi:[1,0]
	s_add_u32 s56, s0, s44
	s_addc_u32 s57, s1, s45
	global_load_dwordx4 v[118:121], v216, s[56:57] nt
	global_load_dwordx4 v[114:117], v216, s[56:57] offset:1024 nt
	s_add_u32 s56, s10, s44
	s_addc_u32 s57, s11, s45
	s_add_i32 m0, s98, 0x1000
	s_nop 0
	global_load_lds_dwordx4 v216, s[56:57] nt
	global_load_dwordx4 v[66:69], v216, s[56:57] offset:1024 nt
	s_add_u32 s56, s0, s46
	s_addc_u32 s57, s1, s47
	global_load_dwordx4 v[62:65], v216, s[56:57] nt
	global_load_dwordx4 v[58:61], v216, s[56:57] offset:1024 nt
	s_add_u32 s56, s10, s46
	s_addc_u32 s57, s11, s47
	s_add_i32 m0, s98, 0x1400
	s_nop 0
	global_load_lds_dwordx4 v216, s[56:57] nt
	global_load_dwordx4 v[18:21], v216, s[56:57] offset:1024 nt
	s_add_u32 s56, s0, s48
	s_addc_u32 s57, s1, s49
	global_load_dwordx4 v[54:57], v216, s[56:57] nt
	global_load_dwordx4 v[50:53], v216, s[56:57] offset:1024 nt
	s_add_u32 s56, s10, s48
	s_addc_u32 s57, s11, s49
	s_add_i32 m0, s98, 0x1800
	s_nop 0
	global_load_lds_dwordx4 v216, s[56:57] nt
	global_load_dwordx4 v[22:25], v216, s[56:57] offset:1024 nt
	s_add_u32 s56, s0, s50
	s_addc_u32 s57, s1, s51
	global_load_dwordx4 v[30:33], v216, s[56:57] nt
	global_load_dwordx4 v[26:29], v216, s[56:57] offset:1024 nt
	s_add_u32 s56, s10, s50
	s_addc_u32 s57, s11, s51
	s_add_i32 m0, s98, 0x1c00
	s_nop 0
	global_load_lds_dwordx4 v216, s[56:57] nt
	global_load_dwordx4 v[6:9], v216, s[56:57] offset:1024 nt
	v_pk_fma_f32 v[184:185], v[184:185], v[138:139], v[200:201] op_sel_hi:[1,0,1]
	v_pk_fma_f32 v[138:139], v[180:181], v[138:139], v[198:199] op_sel_hi:[1,0,1]
	v_pk_fma_f32 v[136:137], v[136:137], v[140:141], v[204:205] op_sel_hi:[1,0,1]
	v_pk_fma_f32 v[134:135], v[134:135], v[140:141], v[202:203] op_sel_hi:[1,0,1]
	v_pk_fma_f32 v[140:141], v[182:183], v[150:151], v[208:209] op_sel_hi:[1,0,1]
	v_pk_fma_f32 v[150:151], v[178:179], v[150:151], v[206:207] op_sel_hi:[1,0,1]
	v_pk_fma_f32 v[148:149], v[148:149], v[152:153], v[212:213] op_sel_hi:[1,0,1]
	v_pk_fma_f32 v[146:147], v[146:147], v[152:153], v[210:211] op_sel_hi:[1,0,1]
	v_pk_fma_f32 v[138:139], v[176:177], v[220:221], v[138:139] op_sel_hi:[1,0,1]
	v_pk_fma_f32 v[152:153], v[174:175], v[220:221], v[184:185] op_sel_hi:[1,0,1]
	v_pk_fma_f32 v[134:135], v[176:177], v[222:223], v[134:135] op_sel_hi:[1,0,1]
	v_pk_fma_f32 v[136:137], v[174:175], v[222:223], v[136:137] op_sel_hi:[1,0,1]
	v_pk_fma_f32 v[150:151], v[168:169], v[224:225], v[150:151] op_sel_hi:[1,0,1]
	v_pk_fma_f32 v[140:141], v[166:167], v[224:225], v[140:141] op_sel_hi:[1,0,1]
	v_pk_fma_f32 v[146:147], v[168:169], v[226:227], v[146:147] op_sel_hi:[1,0,1]
	v_pk_fma_f32 v[148:149], v[166:167], v[226:227], v[148:149] op_sel_hi:[1,0,1]
	v_pk_fma_f32 v[152:153], v[170:171], v[228:229], v[152:153] op_sel_hi:[1,0,1]
	v_pk_fma_f32 v[138:139], v[172:173], v[228:229], v[138:139] op_sel_hi:[1,0,1]
	v_pk_fma_f32 v[166:167], v[170:171], v[230:231], v[136:137] op_sel_hi:[1,0,1]
	v_pk_fma_f32 v[168:169], v[172:173], v[230:231], v[134:135] op_sel_hi:[1,0,1]
	v_pk_fma_f32 v[170:171], v[158:159], v[232:233], v[140:141] op_sel_hi:[1,0,1]
	v_pk_fma_f32 v[150:151], v[160:161], v[232:233], v[150:151] op_sel_hi:[1,0,1]
	v_pk_fma_f32 v[158:159], v[158:159], v[234:235], v[148:149] op_sel_hi:[1,0,1]
	v_pk_fma_f32 v[160:161], v[160:161], v[234:235], v[146:147] op_sel_hi:[1,0,1]
	s_waitcnt vmcnt(33)
	v_pk_fma_f32 v[136:137], v[164:165], v[236:237], v[138:139] op_sel_hi:[1,0,1]
	v_pk_fma_f32 v[134:135], v[162:163], v[236:237], v[152:153] op_sel_hi:[1,0,1]
	v_pk_fma_f32 v[140:141], v[164:165], v[238:239], v[168:169] op_sel_hi:[1,0,1]
	v_pk_fma_f32 v[138:139], v[162:163], v[238:239], v[166:167] op_sel_hi:[1,0,1]
	s_waitcnt vmcnt(32)
	v_pk_fma_f32 v[148:149], v[156:157], v[240:241], v[150:151] op_sel_hi:[1,0,1]
	v_pk_fma_f32 v[146:147], v[154:155], v[240:241], v[170:171] op_sel_hi:[1,0,1]
	v_pk_fma_f32 v[152:153], v[156:157], v[242:243], v[160:161] op_sel_hi:[1,0,1]
	v_pk_fma_f32 v[150:151], v[154:155], v[242:243], v[158:159] op_sel_hi:[1,0,1]
	ds_write_b128 v1, v[134:137]
	ds_write_b128 v1, v[146:149] offset:1024
	ds_write_b128 v1, v[138:141] offset:2048
	ds_write_b128 v1, v[150:153] offset:3072
	s_and_saveexec_b64 s[56:57], s[6:7]
	s_cbranch_execz .LBB0_630
	v_add_u32_e32 v134, 0x8000, v214
	ds_write2_b32 v134, v142, v144 offset1:1
	v_add_u32_e32 v134, 0x8010, v214
	ds_write2_b32 v134, v143, v145 offset1:1
	v_add_u32_e32 v134, 0x8100, v214
	ds_write2_b32 v134, v130, v132 offset1:1
	v_add_u32_e32 v130, 0x8110, v214
	ds_write2_b32 v130, v131, v133 offset1:1

.LBB0_882:
	v_readlane_b32 s0, v245, 2
	v_readlane_b32 s3, v245, 5
	s_bitcmp0_b32 s3, 5
	v_readlane_b32 s85, v245, 50
	v_readlane_b32 s92, v245, 43
	v_readlane_b32 s1, v245, 3
	v_readlane_b32 s2, v245, 4
	s_cbranch_scc1 .LBB0_893
	v_lshrrev_b32_e32 v246, 6, v0
	v_and_b32_e32 v247, 63, v0
	s_nop 0
	v_readfirstlane_b32 s98, v246
	v_lshlrev_b32_e32 v247, 4, v247
	s_lshl_b32 s98, s98, 13
	s_add_i32 s98, s98, 0x9000
	v_add_u32_e32 v246, s98, v247
	s_and_b32 s33, s95, -2
	s_ashr_i32 s1, s95, 31
	s_add_i32 s0, s33, s1
	s_xor_b32 s2, s0, s1
	v_cvt_f32_u32_e32 v1, s2
	v_readlane_b32 s0, v245, 54
	s_lshl_b32 s0, s0, 1
	s_sub_i32 s3, s33, s0
	v_rcp_iflag_f32_e32 v1, v1
	s_addk_i32 s3, 0x6ee
	s_ashr_i32 s4, s3, 31
	s_sub_i32 s5, 0, s2
	v_mul_f32_e32 v1, 0x4f7ffffe, v1
	v_cvt_u32_f32_e32 v1, v1
	s_xor_b32 s20, s4, s1
	s_abs_i32 s3, s3
	v_mov_b32_e32 v131, v0
	v_readfirstlane_b32 s1, v1
	s_mul_i32 s5, s5, s1
	s_mul_hi_u32 s4, s1, s5
	s_add_i32 s1, s1, s4
	s_mul_hi_u32 s1, s3, s1
	s_mul_i32 s4, s1, s2
	s_sub_i32 s3, s3, s4
	s_add_i32 s5, s1, 1
	s_sub_i32 s4, s3, s2
	s_cmp_ge_u32 s3, s2
	s_cselect_b32 s1, s5, s1
	s_cselect_b32 s3, s4, s3
	s_add_i32 s4, s1, 1
	s_cmp_ge_u32 s3, s2
	s_cselect_b32 s1, s4, s1
	s_xor_b32 s21, s1, s20
	s_sub_i32 s77, s21, s20
	s_cmp_lt_i32 s77, 1
	v_readfirstlane_b32 s1, v131
	s_cbranch_scc1 .LBB0_893
	s_add_u32 s10, s96, 0xce00000
	v_readlane_b32 s36, v245, 9
	s_addc_u32 s11, s97, 0
	s_ashr_i32 s16, s1, 6
	s_ashr_i32 s1, s0, 31
	v_readlane_b32 s38, v245, 11
	v_readlane_b32 s39, v245, 12
	s_add_i32 s4, s0, 0x111
	s_lshl_b64 s[0:1], s[0:1], 2
	s_mov_b64 s[14:15], s[38:39]
	s_add_u32 s0, s14, s0
	s_addc_u32 s1, s15, s1
	v_mov_b32_e32 v187, 0
	global_load_dword v1, v187, s[0:1] offset:1092
	s_cmp_lg_u32 s77, 1
	s_cselect_b32 s2, s33, 0
	s_ashr_i32 s3, s2, 31
	s_lshl_b64 s[2:3], s[2:3], 2
	s_add_u32 s0, s0, s2
	s_addc_u32 s1, s1, s3
	s_lshl_b32 s12, s16, 4
	s_ashr_i32 s2, s4, 4
	global_load_dword v22, v187, s[0:1] offset:1092
	s_or_b32 s18, s12, 1
	s_or_b32 s22, s12, 2
	s_or_b32 s24, s12, 3
	s_or_b32 s14, s12, 4
	s_or_b32 s6, s12, 5
	s_or_b32 s0, s12, 6
	s_or_b32 s4, s12, 7
	v_readlane_b32 s37, v245, 10
	v_readlane_b32 s40, v245, 13
	v_readlane_b32 s41, v245, 14
	v_readlane_b32 s42, v245, 15
	v_readlane_b32 s43, v245, 16
	v_readlane_b32 s44, v245, 17
	v_readlane_b32 s45, v245, 18
	v_readlane_b32 s46, v245, 19
	v_readlane_b32 s47, v245, 20
	v_readlane_b32 s48, v245, 21
	v_readlane_b32 s49, v245, 22
	s_ashr_i32 s13, s12, 31
	s_ashr_i32 s3, s2, 31
	s_ashr_i32 s19, s18, 31
	s_ashr_i32 s23, s22, 31
	s_ashr_i32 s25, s24, 31
	s_ashr_i32 s15, s14, 31
	s_ashr_i32 s7, s6, 31
	s_ashr_i32 s1, s0, 31
	s_ashr_i32 s5, s4, 31
	s_lshl_b64 s[30:31], s[12:13], 9
	s_lshl_b64 s[2:3], s[2:3], 10
	s_lshl_b64 s[36:37], s[18:19], 9
	s_lshl_b64 s[38:39], s[22:23], 9
	s_lshl_b64 s[40:41], s[24:25], 9
	s_lshl_b64 s[42:43], s[14:15], 9
	s_lshl_b64 s[44:45], s[6:7], 9
	s_lshl_b64 s[46:47], s[0:1], 9
	s_lshl_b64 s[48:49], s[4:5], 9
	v_and_b32_e32 v130, 63, v131
	s_add_u32 s2, s10, s2
	v_lshlrev_b32_e32 v186, 3, v130
	s_addc_u32 s3, s11, s3
	s_waitcnt vmcnt(0)
	v_lshl_add_u64 v[10:11], s[2:3], 0, v[186:187]
	v_readlane_b32 s50, v245, 23
	v_readlane_b32 s51, v245, 24
	v_lshlrev_b32_e32 v136, 4, v130
	s_mov_b32 s82, 0x1000000
	v_add_co_u32_e32 v12, vcc, s82, v10
	v_bfe_u32 v132, v131, 2, 4
	s_nop 0
	v_addc_co_u32_e32 v13, vcc, 0, v11, vcc
	v_ashrrev_i32_e32 v135, 6, v131
	v_bfe_u32 v138, v131, 5, 1
	v_ashrrev_i32_e32 v137, 7, v131
	v_and_b32_e32 v134, 31, v131
	v_lshl_add_u32 v216, v131, 2, 0
	v_lshl_add_u64 v[188:189], s[10:11], 0, v[186:187]
	v_lshlrev_b32_e32 v186, 4, v134
	v_lshl_add_u32 v139, v135, 10, 0
	s_mov_b64 s[10:11], 0x23201120
	v_mov_b32_e32 v133, v187
	s_mov_b32 s87, s85
	s_mov_b32 s68, 2
	s_mov_b32 s76, 0xff800000
	v_add_u32_e32 v217, v139, v136
	v_readfirstlane_b32 s2, v1
	s_ashr_i32 s3, s2, 31
	s_lshl_b64 s[2:3], s[2:3], 18
	s_add_u32 s50, s80, s2
	s_addc_u32 s51, s81, s3
	s_lshl_b64 s[4:5], s[4:5], 11
	s_add_u32 s8, s50, s4
	s_addc_u32 s9, s51, s5
	global_load_dwordx4 v[6:9], v136, s[8:9] offset:1024 nt
	s_add_i32 m0, s98, 0x1c00
	s_nop 0
	global_load_lds_dwordx4 v136, s[8:9] nt
	s_add_u32 s8, s78, s2
	s_addc_u32 s9, s79, s3
	s_add_u32 s28, s8, s4
	s_addc_u32 s29, s9, s5
	s_lshl_b64 s[4:5], s[12:13], 11
	s_add_u32 s2, s8, s4
	s_addc_u32 s3, s9, s5
	s_lshl_b64 s[18:19], s[18:19], 11
	global_load_dwordx4 v[66:69], v136, s[28:29] offset:1024 nt
	global_load_dwordx4 v[70:73], v136, s[28:29] nt
	s_add_u32 s28, s8, s18
	s_addc_u32 s29, s9, s19
	s_lshl_b64 s[22:23], s[22:23], 11
	s_add_u32 s56, s8, s22
	s_addc_u32 s57, s9, s23
	s_lshl_b64 s[24:25], s[24:25], 11
	s_add_u32 s58, s8, s24
	s_addc_u32 s59, s9, s25
	s_lshl_b64 s[14:15], s[14:15], 11
	s_add_u32 s72, s8, s14
	s_addc_u32 s73, s9, s15
	s_lshl_b64 s[6:7], s[6:7], 11
	s_add_u32 s74, s8, s6
	s_addc_u32 s75, s9, s7
	s_lshl_b64 s[0:1], s[0:1], 11
	s_add_u32 s52, s8, s0
	s_addc_u32 s53, s9, s1
	global_load_dwordx4 v[74:77], v136, s[52:53] nt
	global_load_dwordx4 v[78:81], v136, s[52:53] offset:1024 nt
	s_add_u32 s52, s50, s0
	s_addc_u32 s53, s51, s1
	s_mov_b64 s[0:1], 0x1000000
	v_lshl_add_u64 v[10:11], v[10:11], 0, s[0:1]
	global_load_dwordx2 v[14:15], v[10:11], off offset:512
	global_load_dwordx2 v[16:17], v[12:13], off
	s_add_u32 s6, s50, s6
	s_addc_u32 s7, s51, s7
	global_load_dwordx4 v[18:21], v136, s[52:53] offset:1024 nt
	s_add_i32 m0, s98, 0x1800
	s_nop 0
	global_load_lds_dwordx4 v136, s[52:53] nt
	v_readfirstlane_b32 s26, v22
	s_movk_i32 s53, 0x88
	s_waitcnt vmcnt(3)
	v_lshlrev_b32_e32 v219, 16, v14
	v_and_b32_e32 v220, 0xffff0000, v14
	v_lshlrev_b32_e32 v198, 16, v15
	v_and_b32_e32 v199, 0xffff0000, v15
	s_waitcnt vmcnt(2)
	v_lshlrev_b32_e32 v221, 16, v16
	v_and_b32_e32 v222, 0xffff0000, v16
	v_lshlrev_b32_e32 v200, 16, v17
	v_and_b32_e32 v201, 0xffff0000, v17
	global_load_dwordx4 v[22:25], v136, s[6:7] offset:1024 nt
	s_add_i32 m0, s98, 0x1400
	s_nop 0
	global_load_lds_dwordx4 v136, s[6:7] nt
	global_load_dwordx4 v[102:105], v136, s[74:75] nt
	global_load_dwordx4 v[98:101], v136, s[74:75] offset:1024 nt
	s_add_u32 s6, s50, s14
	s_addc_u32 s7, s51, s15
	global_load_dwordx4 v[58:61], v136, s[6:7] offset:1024 nt
	s_add_i32 m0, s98, 0x1000
	s_nop 0
	global_load_lds_dwordx4 v136, s[6:7] nt
	global_load_dwordx4 v[118:121], v136, s[72:73] nt
	global_load_dwordx4 v[114:117], v136, s[72:73] offset:1024 nt
	s_add_u32 s6, s50, s24
	s_addc_u32 s7, s51, s25
	global_load_dwordx4 v[42:45], v136, s[6:7] offset:1024 nt
	s_add_i32 m0, s98, 0xc00
	s_nop 0
	global_load_lds_dwordx4 v136, s[6:7] nt
	global_load_dwordx4 v[86:89], v136, s[58:59] nt
	global_load_dwordx4 v[82:85], v136, s[58:59] offset:1024 nt
	s_add_u32 s6, s50, s22
	s_addc_u32 s7, s51, s23
	global_load_dwordx4 v[46:49], v136, s[6:7] offset:1024 nt
	s_add_i32 m0, s98, 0x800
	s_nop 0
	global_load_lds_dwordx4 v136, s[6:7] nt
	global_load_dwordx4 v[94:97], v136, s[56:57] nt
	global_load_dwordx4 v[90:93], v136, s[56:57] offset:1024 nt
	s_add_u32 s6, s50, s18
	s_addc_u32 s7, s51, s19
	s_add_u32 s4, s50, s4
	s_addc_u32 s5, s51, s5
	global_load_dwordx4 v[50:53], v136, s[6:7] offset:1024 nt
	s_add_i32 m0, s98, 0x400
	s_nop 0
	global_load_lds_dwordx4 v136, s[6:7] nt
	global_load_dwordx4 v[110:113], v136, s[28:29] nt
	global_load_dwordx4 v[106:109], v136, s[28:29] offset:1024 nt
	global_load_dwordx4 v[54:57], v136, s[4:5] offset:1024 nt
	s_add_i32 m0, s98, 0x0
	s_nop 0
	global_load_lds_dwordx4 v136, s[4:5] nt
	global_load_dwordx4 v[126:129], v136, s[2:3] nt
	global_load_dwordx4 v[122:125], v136, s[2:3] offset:1024 nt
	s_lshl_b32 s2, s16, 12
	s_add_i32 s4, s2, 0
	s_mulk_i32 s16, 0xf020
	v_add_u32_e32 v1, s4, v136
	s_add_i32 s4, s4, s16
	v_add_u32_e32 v214, s4, v132
	v_lshlrev_b32_e32 v132, 1, v135
	v_and_or_b32 v132, v132, 2, v138
	v_lshl_add_u32 v132, v132, 1, v137
	s_movk_i32 s6, 0x100
	v_lshl_add_u32 v215, v132, 2, 0
	v_and_b32_e32 v132, -8, v131
	v_cmp_gt_i32_e64 s[4:5], s6, v131
	v_cmp_eq_u32_e64 s[6:7], s6, v132
	v_mul_lo_u32 v132, v131, s53
	v_lshlrev_b32_e32 v131, 2, v135
	v_cmp_eq_u32_e64 s[2:3], 0, v134
	v_and_b32_e32 v131, 4, v131
	v_lshlrev_b32_e32 v134, 1, v138
	v_add3_u32 v131, v137, v131, v134
	v_mul_lo_u32 v134, v131, s53
	v_ashrrev_i32_e32 v135, 31, v134
	v_lshl_add_u64 v[134:135], v[134:135], 2, v[186:187]
	v_lshl_add_u64 v[190:191], v[134:135], 0, s[10:11]
	v_readlane_b32 s10, v245, 51
	s_lshl_b32 s10, s10, 1
	v_readlane_b32 s11, v245, 52
	s_or_b32 s14, s12, 8
	s_or_b32 s22, s12, 12
	s_or_b32 s16, s12, 9
	s_or_b32 s18, s12, 10
	s_or_b32 s24, s12, 11
	s_or_b32 s28, s12, 13
	s_or_b32 s56, s12, 14
	s_or_b32 s12, s12, 15
	s_andn2_b32 s10, s10, 63
	s_lshl_b32 s11, s11, 1
	s_ashr_i32 s13, s12, 31
	s_or_b32 s10, s10, s11
	s_ashr_i32 s15, s14, 31
	s_ashr_i32 s17, s16, 31
	s_ashr_i32 s19, s18, 31
	s_ashr_i32 s25, s24, 31
	s_ashr_i32 s23, s22, 31
	s_ashr_i32 s29, s28, 31
	s_ashr_i32 s57, s56, 31
	s_lshl_b64 s[58:59], s[12:13], 9
	s_add_i32 s12, s10, 0x110
	s_lshl_b32 s69, s33, 1
	s_lshl_b64 s[14:15], s[14:15], 9
	s_lshl_b64 s[16:17], s[16:17], 9
	s_lshl_b64 s[18:19], s[18:19], 9
	s_lshl_b64 s[24:25], s[24:25], 9
	s_lshl_b64 s[22:23], s[22:23], 9
	s_lshl_b64 s[28:29], s[28:29], 9
	s_lshl_b64 s[56:57], s[56:57], 9
	s_ashr_i32 s72, s12, 31
	s_mul_i32 s10, s12, 0x1100
	v_add_u32_e32 v132, 0xffff7800, v132
	s_mul_hi_i32 s11, s12, 0x1100
	s_add_u32 s10, s96, s10
	s_addc_u32 s11, s97, s11
	s_ashr_i32 s73, s33, 31
	v_lshlrev_b64 v[192:193], 2, v[132:133]
	s_or_b32 s74, s12, 1
	s_sub_i32 s75, s20, s21
	s_lshl_b64 s[12:13], s[14:15], 2
	v_lshlrev_b32_e32 v186, 4, v130
	s_lshl_b64 s[14:15], s[16:17], 2
	s_lshl_b64 s[16:17], s[18:19], 2
	s_lshl_b64 s[18:19], s[24:25], 2
	s_lshl_b64 s[20:21], s[22:23], 2
	s_lshl_b64 s[22:23], s[28:29], 2
	s_lshl_b64 s[24:25], s[56:57], 2
	s_lshl_b64 s[28:29], s[58:59], 2
	s_lshl_b64 s[30:31], s[30:31], 2
	s_lshl_b64 s[36:37], s[36:37], 2
	s_lshl_b64 s[38:39], s[38:39], 2
	s_lshl_b64 s[40:41], s[40:41], 2
	s_lshl_b64 s[42:43], s[42:43], 2
	s_lshl_b64 s[44:45], s[44:45], 2
	s_lshl_b64 s[46:47], s[46:47], 2
	s_lshl_b64 s[48:49], s[48:49], 2
	s_branch .LBB0_886

.LBB0_886:
	s_add_i32 s83, s68, -1
	s_add_i32 s86, s33, s74
	s_cmp_lt_i32 s68, s77
	s_cselect_b32 s56, s69, 0
	s_ashr_i32 s27, s26, 31
	s_ashr_i32 s57, s56, 31
	s_add_u32 s56, s74, s56
	s_addc_u32 s57, s72, s57
	s_lshl_b64 s[84:85], s[56:57], 2
	v_readlane_b32 s52, v245, 9
	v_readlane_b32 s54, v245, 11
	v_readlane_b32 s56, v245, 13
	v_readlane_b32 s55, v245, 12
	v_readlane_b32 s57, v245, 14
	s_add_u32 s56, s54, s84
	s_addc_u32 s57, s55, s85
	s_cmp_lt_i32 s83, s77
	v_readlane_b32 s53, v245, 10
	v_readlane_b32 s58, v245, 15
	global_load_dword v218, v187, s[56:57]
	s_cselect_b32 s56, s86, s74
	s_ashr_i32 s56, s56, 4
	s_ashr_i32 s57, s56, 31
	s_lshl_b64 s[56:57], s[56:57], 10
	v_lshl_add_u64 v[130:131], v[188:189], 0, s[56:57]
	v_lshl_add_u64 v[132:133], v[130:131], 0, s[0:1]
	v_add_co_u32_e32 v130, vcc, s82, v130
	v_readlane_b32 s59, v245, 16
	s_nop 0
	v_addc_co_u32_e32 v131, vcc, 0, v131, vcc
	global_load_dwordx2 v[196:197], v[130:131], off
	global_load_dwordx2 v[194:195], v[132:133], off offset:512
	v_readlane_b32 s60, v245, 17
	v_readlane_b32 s61, v245, 18
	v_readlane_b32 s62, v245, 19
	v_readlane_b32 s63, v245, 20
	v_readlane_b32 s64, v245, 21
	v_readlane_b32 s65, v245, 22
	v_readlane_b32 s66, v245, 23
	v_readlane_b32 s67, v245, 24
	s_mov_b64 s[56:57], s[50:51]
	s_mov_b64 s[58:59], s[8:9]
	s_waitcnt vmcnt(4)
	ds_read_b128 v[2:5], v246 offset:7168
	ds_read_b128 v[10:13], v246 offset:6144
	ds_read_b128 v[14:17], v246 offset:5120
	ds_read_b128 v[26:29], v246 offset:3072
	ds_read_b128 v[30:33], v246 offset:0
	ds_read_b128 v[34:37], v246 offset:1024
	ds_read_b128 v[38:41], v246 offset:2048
	ds_read_b128 v[62:65], v246 offset:4096
	s_waitcnt lgkmcnt(0)
	v_mul_f32_e32 v130, v222, v127
	v_fmac_f32_e32 v130, v221, v126
	v_pk_mul_f32 v[126:127], v[200:201], v[128:129]
	s_lshl_b64 s[50:51], s[26:27], 18
	v_add_f32_e32 v126, v126, v130
	v_add_f32_e32 v126, v127, v126
	s_waitcnt vmcnt(3)
	v_mul_f32_e32 v127, v123, v220
	v_fmac_f32_e32 v127, v122, v219
	v_pk_mul_f32 v[122:123], v[124:125], v[198:199]
	s_add_u32 s8, s78, s50
	v_add_f32_e32 v122, v122, v127
	v_add_f32_e32 v122, v123, v122
	v_add_f32_dpp v123, v126, v126 quad_perm:[1,0,3,2] row_mask:0xf bank_mask:0xf bound_ctrl:1
	v_mul_f32_e32 v126, v222, v111
	v_fmac_f32_e32 v126, v221, v110
	v_pk_mul_f32 v[110:111], v[200:201], v[112:113]
	v_add_f32_dpp v123, v123, v123 quad_perm:[2,3,0,1] row_mask:0xf bank_mask:0xf bound_ctrl:1
	v_add_f32_e32 v110, v110, v126
	v_add_f32_e32 v110, v111, v110
	v_mul_f32_e32 v111, v107, v220
	v_fmac_f32_e32 v111, v106, v219
	v_pk_mul_f32 v[106:107], v[108:109], v[198:199]
	v_add_f32_dpp v122, v122, v122 quad_perm:[1,0,3,2] row_mask:0xf bank_mask:0xf bound_ctrl:1
	v_add_f32_e32 v106, v106, v111
	v_add_f32_e32 v106, v107, v106
	v_add_f32_dpp v107, v110, v110 quad_perm:[1,0,3,2] row_mask:0xf bank_mask:0xf bound_ctrl:1
	v_mul_f32_e32 v110, v222, v95
	v_fmac_f32_e32 v110, v221, v94
	v_pk_mul_f32 v[94:95], v[200:201], v[96:97]
	v_add_f32_dpp v107, v107, v107 quad_perm:[2,3,0,1] row_mask:0xf bank_mask:0xf bound_ctrl:1
	v_add_f32_e32 v94, v94, v110
	v_add_f32_e32 v94, v95, v94
	v_mul_f32_e32 v95, v91, v220
	v_fmac_f32_e32 v95, v90, v219
	v_pk_mul_f32 v[90:91], v[92:93], v[198:199]
	v_add_f32_dpp v106, v106, v106 quad_perm:[1,0,3,2] row_mask:0xf bank_mask:0xf bound_ctrl:1
	v_add_f32_e32 v90, v90, v95
	v_add_f32_e32 v90, v91, v90
	v_add_f32_dpp v91, v94, v94 quad_perm:[1,0,3,2] row_mask:0xf bank_mask:0xf bound_ctrl:1
	v_mul_f32_e32 v94, v222, v87
	v_fmac_f32_e32 v94, v221, v86
	v_pk_mul_f32 v[86:87], v[200:201], v[88:89]
	v_add_f32_dpp v123, v123, v123 row_ror:4 row_mask:0xf bank_mask:0xf bound_ctrl:1
	v_add_f32_e32 v86, v86, v94
	v_add_f32_e32 v86, v87, v86
	v_mul_f32_e32 v87, v83, v220
	v_fmac_f32_e32 v87, v82, v219
	v_pk_mul_f32 v[82:83], v[84:85], v[198:199]
	v_add_f32_dpp v122, v122, v122 quad_perm:[2,3,0,1] row_mask:0xf bank_mask:0xf bound_ctrl:1
	v_add_f32_e32 v82, v82, v87
	v_add_f32_e32 v82, v83, v82
	v_add_f32_dpp v83, v86, v86 quad_perm:[1,0,3,2] row_mask:0xf bank_mask:0xf bound_ctrl:1
	v_add_f32_dpp v107, v107, v107 row_ror:4 row_mask:0xf bank_mask:0xf bound_ctrl:1
	v_add_f32_dpp v106, v106, v106 quad_perm:[2,3,0,1] row_mask:0xf bank_mask:0xf bound_ctrl:1
	v_add_f32_dpp v91, v91, v91 quad_perm:[2,3,0,1] row_mask:0xf bank_mask:0xf bound_ctrl:1
	v_add_f32_dpp v90, v90, v90 quad_perm:[1,0,3,2] row_mask:0xf bank_mask:0xf bound_ctrl:1
	v_add_f32_dpp v83, v83, v83 quad_perm:[2,3,0,1] row_mask:0xf bank_mask:0xf bound_ctrl:1
	v_add_f32_dpp v82, v82, v82 quad_perm:[1,0,3,2] row_mask:0xf bank_mask:0xf bound_ctrl:1
	v_add_f32_dpp v123, v123, v123 row_ror:8 row_mask:0xf bank_mask:0xf bound_ctrl:1
	v_add_f32_dpp v122, v122, v122 row_ror:4 row_mask:0xf bank_mask:0xf bound_ctrl:1
	v_add_f32_dpp v107, v107, v107 row_ror:8 row_mask:0xf bank_mask:0xf bound_ctrl:1
	v_add_f32_dpp v106, v106, v106 row_ror:4 row_mask:0xf bank_mask:0xf bound_ctrl:1
	v_add_f32_dpp v91, v91, v91 row_ror:4 row_mask:0xf bank_mask:0xf bound_ctrl:1
	v_add_f32_dpp v90, v90, v90 quad_perm:[2,3,0,1] row_mask:0xf bank_mask:0xf bound_ctrl:1
	v_add_f32_dpp v83, v83, v83 row_ror:4 row_mask:0xf bank_mask:0xf bound_ctrl:1
	v_add_f32_dpp v82, v82, v82 quad_perm:[2,3,0,1] row_mask:0xf bank_mask:0xf bound_ctrl:1
	v_add_f32_dpp v122, v122, v122 row_ror:8 row_mask:0xf bank_mask:0xf bound_ctrl:1
	v_mov_b32_e32 v124, v123
	v_add_f32_dpp v106, v106, v106 row_ror:8 row_mask:0xf bank_mask:0xf bound_ctrl:1
	v_mov_b32_e32 v108, v107
	v_add_f32_dpp v91, v91, v91 row_ror:8 row_mask:0xf bank_mask:0xf bound_ctrl:1
	v_add_f32_dpp v90, v90, v90 row_ror:4 row_mask:0xf bank_mask:0xf bound_ctrl:1
	v_add_f32_dpp v88, v83, v83 row_ror:8 row_mask:0xf bank_mask:0xf bound_ctrl:1
	v_add_f32_dpp v82, v82, v82 row_ror:4 row_mask:0xf bank_mask:0xf bound_ctrl:1
	v_permlane16_swap_b32_e32 v123, v124
	v_mov_b32_e32 v125, v122
	v_permlane16_swap_b32_e32 v107, v108
	v_mov_b32_e32 v109, v106
	v_add_f32_dpp v90, v90, v90 row_ror:8 row_mask:0xf bank_mask:0xf bound_ctrl:1
	v_mov_b32_e32 v92, v91
	v_add_f32_dpp v89, v82, v82 row_ror:8 row_mask:0xf bank_mask:0xf bound_ctrl:1
	v_mov_b32_e32 v94, v88
	v_permlane16_swap_b32_e32 v122, v125
	v_permlane16_swap_b32_e32 v106, v109
	v_permlane16_swap_b32_e32 v91, v92
	v_mov_b32_e32 v93, v90
	v_permlane16_swap_b32_e32 v88, v94
	v_mov_b32_e32 v95, v89
	v_max3_f32 v82, v123, s76, v107
	v_permlane16_swap_b32_e32 v90, v93
	v_permlane16_swap_b32_e32 v89, v95
	v_max3_f32 v83, v124, s76, v108
	v_max3_f32 v84, v122, s76, v106
	v_max3_f32 v155, v82, v91, v88
	v_max3_f32 v157, v83, v92, v94
	v_max3_f32 v159, v84, v90, v89
	v_sub_f32_e32 v82, 0xff800000, v155
	v_sub_f32_e32 v84, v123, v155
	v_max3_f32 v85, v125, s76, v109
	v_exp_f32_e32 v83, v82
	v_sub_f32_e32 v82, 0xff800000, v157
	v_exp_f32_e32 v164, v84
	v_sub_f32_e32 v84, v124, v157
	v_max3_f32 v165, v85, v93, v95
	v_exp_f32_e32 v85, v82
	v_sub_f32_e32 v82, 0xff800000, v159
	v_exp_f32_e32 v156, v84
	v_sub_f32_e32 v84, v122, v159
	v_exp_f32_e32 v86, v82
	v_sub_f32_e32 v82, 0xff800000, v165
	v_exp_f32_e32 v166, v84
	v_sub_f32_e32 v84, v125, v165
	v_exp_f32_e32 v87, v82
	v_exp_f32_e32 v84, v84
	v_mul_f32_e32 v154, 0, v85
	v_fma_f32 v85, 0, v85, v156
	v_mul_f32_e32 v82, 0, v87
	v_mov_b32_e32 v110, v84
	v_mul_f32_e32 v160, 0, v83
	v_mul_f32_e32 v162, 0, v86
	v_fma_f32 v96, 0, v83, v164
	v_fma_f32 v97, 0, v86, v166
	v_fmac_f32_e32 v110, 0, v87
	v_pk_fma_f32 v[86:87], v[54:55], v[84:85], v[82:83] op_sel_hi:[1,0,0]
	v_pk_fma_f32 v[82:83], v[56:57], v[84:85], v[82:83] op_sel_hi:[1,0,0]
	v_sub_f32_e32 v84, v107, v155
	v_exp_f32_e32 v168, v84
	v_sub_f32_e32 v84, v108, v157
	v_exp_f32_e32 v158, v84
	v_sub_f32_e32 v84, v106, v159
	v_exp_f32_e32 v170, v84
	v_sub_f32_e32 v84, v109, v165
	v_exp_f32_e32 v84, v84
	v_add_f32_e32 v106, v158, v85
	v_add_f32_e32 v96, v168, v96
	v_add_f32_e32 v97, v170, v97
	v_add_f32_e32 v107, v84, v110
	v_pk_fma_f32 v[82:83], v[52:53], v[84:85], v[82:83] op_sel_hi:[1,0,1]
	v_pk_fma_f32 v[84:85], v[50:51], v[84:85], v[86:87] op_sel_hi:[1,0,1]
	v_sub_f32_e32 v86, v91, v155
	v_exp_f32_e32 v172, v86
	v_sub_f32_e32 v86, v92, v157
	v_exp_f32_e32 v174, v86
	v_sub_f32_e32 v86, v90, v159
	v_exp_f32_e32 v176, v86
	v_sub_f32_e32 v86, v93, v165
	v_exp_f32_e32 v86, v86
	v_add_f32_e32 v87, v172, v96
	v_add_f32_e32 v90, v174, v106
	v_add_f32_e32 v91, v176, v97
	v_add_f32_e32 v92, v86, v107
	v_pk_fma_f32 v[84:85], v[46:47], v[86:87], v[84:85] op_sel_hi:[1,0,1]
	v_pk_fma_f32 v[82:83], v[48:49], v[86:87], v[82:83] op_sel_hi:[1,0,1]
	v_sub_f32_e32 v86, v88, v155
	v_exp_f32_e32 v206, v86
	v_sub_f32_e32 v86, v94, v157
	v_exp_f32_e32 v208, v86
	v_sub_f32_e32 v86, v89, v159
	v_exp_f32_e32 v210, v86
	v_sub_f32_e32 v86, v95, v165
	v_exp_f32_e32 v86, v86
	s_addc_u32 s9, s79, s51
	v_add_f32_e32 v167, v206, v87
	v_add_f32_e32 v169, v208, v90
	v_add_f32_e32 v171, v210, v91
	v_add_f32_e32 v173, v86, v92
	v_pk_fma_f32 v[202:203], v[44:45], v[86:87], v[82:83] op_sel_hi:[1,0,1]
	v_pk_fma_f32 v[204:205], v[42:43], v[86:87], v[84:85] op_sel_hi:[1,0,1]
	s_add_u32 s52, s58, s12
	s_addc_u32 s53, s59, s13
	global_load_dwordx4 v[182:185], v186, s[52:53] nt
	global_load_dwordx4 v[178:181], v186, s[52:53] offset:1024 nt
	s_add_u32 s52, s56, s12
	s_addc_u32 s53, s57, s13
	s_add_i32 m0, s98, 0x0
	s_nop 0
	global_load_lds_dwordx4 v186, s[52:53] nt
	global_load_dwordx4 v[82:85], v186, s[52:53] offset:1024 nt
	s_add_u32 s52, s58, s14
	s_addc_u32 s53, s59, s15
	global_load_dwordx4 v[126:129], v186, s[52:53] nt
	global_load_dwordx4 v[122:125], v186, s[52:53] offset:1024 nt
	s_add_u32 s52, s56, s14
	s_addc_u32 s53, s57, s15
	s_add_i32 m0, s98, 0x400
	s_nop 0
	global_load_lds_dwordx4 v186, s[52:53] nt
	global_load_dwordx4 v[142:145], v186, s[52:53] offset:1024 nt
	s_add_u32 s52, s58, s16
	s_addc_u32 s53, s59, s17
	global_load_dwordx4 v[110:113], v186, s[52:53] nt
	global_load_dwordx4 v[106:109], v186, s[52:53] offset:1024 nt
	s_add_u32 s52, s56, s16
	s_addc_u32 s53, s57, s17
	s_add_i32 m0, s98, 0x800
	s_nop 0
	global_load_lds_dwordx4 v186, s[52:53] nt
	global_load_dwordx4 v[146:149], v186, s[52:53] offset:1024 nt
	s_add_u32 s52, s58, s18
	s_addc_u32 s53, s59, s19
	global_load_dwordx4 v[94:97], v186, s[52:53] nt
	global_load_dwordx4 v[90:93], v186, s[52:53] offset:1024 nt
	s_add_u32 s52, s56, s18
	s_addc_u32 s53, s57, s19
	s_add_i32 m0, s98, 0xc00
	s_nop 0
	global_load_lds_dwordx4 v186, s[52:53] nt
	global_load_dwordx4 v[150:153], v186, s[52:53] offset:1024 nt
	v_pk_fma_f32 v[212:213], v[30:31], v[164:165], v[160:161] op_sel_hi:[1,0,0]
	v_pk_fma_f32 v[160:161], v[32:33], v[164:165], v[160:161] op_sel_hi:[1,0,0]
	v_pk_fma_f32 v[54:55], v[54:55], v[166:167], v[162:163] op_sel_hi:[1,0,0]
	v_pk_fma_f32 v[56:57], v[56:57], v[166:167], v[162:163] op_sel_hi:[1,0,0]
	v_pk_fma_f32 v[160:161], v[36:37], v[168:169], v[160:161] op_sel_hi:[1,0,1]
	v_pk_fma_f32 v[162:163], v[34:35], v[168:169], v[212:213] op_sel_hi:[1,0,1]
	v_pk_fma_f32 v[52:53], v[52:53], v[170:171], v[56:57] op_sel_hi:[1,0,1]
	v_pk_fma_f32 v[50:51], v[50:51], v[170:171], v[54:55] op_sel_hi:[1,0,1]
	v_pk_fma_f32 v[54:55], v[38:39], v[172:173], v[162:163] op_sel_hi:[1,0,1]
	v_pk_fma_f32 v[56:57], v[40:41], v[172:173], v[160:161] op_sel_hi:[1,0,1]
	v_pk_fma_f32 v[50:51], v[46:47], v[176:177], v[50:51] op_sel_hi:[1,0,1]
	v_pk_fma_f32 v[52:53], v[48:49], v[176:177], v[52:53] op_sel_hi:[1,0,1]
	v_pk_fma_f32 v[46:47], v[28:29], v[206:207], v[56:57] op_sel_hi:[1,0,1]
	v_pk_fma_f32 v[48:49], v[26:27], v[206:207], v[54:55] op_sel_hi:[1,0,1]
	v_pk_fma_f32 v[44:45], v[44:45], v[210:211], v[52:53] op_sel_hi:[1,0,1]
	v_pk_fma_f32 v[42:43], v[42:43], v[210:211], v[50:51] op_sel_hi:[1,0,1]
	v_mul_f32_e32 v52, v222, v119
	v_fmac_f32_e32 v52, v221, v118
	v_pk_mul_f32 v[50:51], v[200:201], v[120:121]
	v_mul_f32_e32 v53, v115, v220
	v_add_f32_e32 v50, v50, v52
	v_add_f32_e32 v52, v51, v50
	v_fmac_f32_e32 v53, v114, v219
	v_pk_mul_f32 v[50:51], v[116:117], v[198:199]
	v_mul_f32_e32 v57, v99, v220
	v_add_f32_e32 v50, v50, v53
	v_add_f32_e32 v50, v51, v50
	v_add_f32_dpp v51, v52, v52 quad_perm:[1,0,3,2] row_mask:0xf bank_mask:0xf bound_ctrl:1
	v_mul_f32_e32 v52, v222, v103
	v_add_f32_dpp v50, v50, v50 quad_perm:[1,0,3,2] row_mask:0xf bank_mask:0xf bound_ctrl:1
	v_add_f32_dpp v51, v51, v51 quad_perm:[2,3,0,1] row_mask:0xf bank_mask:0xf bound_ctrl:1
	v_fmac_f32_e32 v52, v221, v102
	v_add_f32_dpp v50, v50, v50 quad_perm:[2,3,0,1] row_mask:0xf bank_mask:0xf bound_ctrl:1
	v_add_f32_dpp v51, v51, v51 row_ror:4 row_mask:0xf bank_mask:0xf bound_ctrl:1
	v_fmac_f32_e32 v57, v98, v219
	v_add_f32_dpp v50, v50, v50 row_ror:4 row_mask:0xf bank_mask:0xf bound_ctrl:1
	v_add_f32_dpp v53, v51, v51 row_ror:8 row_mask:0xf bank_mask:0xf bound_ctrl:1
	v_pk_fma_f32 v[30:31], v[30:31], v[156:157], v[154:155] op_sel_hi:[1,0,0]
	v_add_f32_dpp v54, v50, v50 row_ror:8 row_mask:0xf bank_mask:0xf bound_ctrl:1
	v_pk_mul_f32 v[50:51], v[200:201], v[104:105]
	v_mov_b32_e32 v56, v54
	v_add_f32_e32 v50, v50, v52
	v_add_f32_e32 v52, v51, v50
	v_pk_mul_f32 v[50:51], v[100:101], v[198:199]
	v_permlane16_swap_b32_e32 v54, v56
	v_add_f32_e32 v50, v50, v57
	v_add_f32_e32 v50, v51, v50
	v_add_f32_dpp v51, v52, v52 quad_perm:[1,0,3,2] row_mask:0xf bank_mask:0xf bound_ctrl:1
	v_mul_f32_e32 v52, v222, v75
	v_add_f32_dpp v50, v50, v50 quad_perm:[1,0,3,2] row_mask:0xf bank_mask:0xf bound_ctrl:1
	v_add_f32_dpp v51, v51, v51 quad_perm:[2,3,0,1] row_mask:0xf bank_mask:0xf bound_ctrl:1
	v_fmac_f32_e32 v52, v221, v74
	v_add_f32_dpp v50, v50, v50 quad_perm:[2,3,0,1] row_mask:0xf bank_mask:0xf bound_ctrl:1
	v_add_f32_dpp v51, v51, v51 row_ror:4 row_mask:0xf bank_mask:0xf bound_ctrl:1
	v_mul_f32_e32 v57, v79, v220
	v_add_f32_dpp v50, v50, v50 row_ror:4 row_mask:0xf bank_mask:0xf bound_ctrl:1
	v_add_f32_dpp v98, v51, v51 row_ror:8 row_mask:0xf bank_mask:0xf bound_ctrl:1
	v_fmac_f32_e32 v57, v78, v219
	v_add_f32_dpp v99, v50, v50 row_ror:8 row_mask:0xf bank_mask:0xf bound_ctrl:1
	v_pk_mul_f32 v[50:51], v[200:201], v[76:77]
	v_mov_b32_e32 v101, v99
	v_add_f32_e32 v50, v50, v52
	v_add_f32_e32 v52, v51, v50
	v_pk_mul_f32 v[50:51], v[80:81], v[198:199]
	v_permlane16_swap_b32_e32 v99, v101
	v_add_f32_e32 v50, v50, v57
	v_add_f32_e32 v50, v51, v50
	v_add_f32_dpp v51, v52, v52 quad_perm:[1,0,3,2] row_mask:0xf bank_mask:0xf bound_ctrl:1
	v_mul_f32_e32 v52, v222, v71
	v_add_f32_dpp v50, v50, v50 quad_perm:[1,0,3,2] row_mask:0xf bank_mask:0xf bound_ctrl:1
	v_add_f32_dpp v51, v51, v51 quad_perm:[2,3,0,1] row_mask:0xf bank_mask:0xf bound_ctrl:1
	v_fmac_f32_e32 v52, v221, v70
	v_add_f32_dpp v50, v50, v50 quad_perm:[2,3,0,1] row_mask:0xf bank_mask:0xf bound_ctrl:1
	v_add_f32_dpp v51, v51, v51 row_ror:4 row_mask:0xf bank_mask:0xf bound_ctrl:1
	v_mul_f32_e32 v57, v67, v220
	v_add_f32_dpp v50, v50, v50 row_ror:4 row_mask:0xf bank_mask:0xf bound_ctrl:1
	v_add_f32_dpp v74, v51, v51 row_ror:8 row_mask:0xf bank_mask:0xf bound_ctrl:1
	v_fmac_f32_e32 v57, v66, v219
	v_add_f32_dpp v75, v50, v50 row_ror:8 row_mask:0xf bank_mask:0xf bound_ctrl:1
	v_pk_mul_f32 v[50:51], v[200:201], v[72:73]
	v_mov_b32_e32 v77, v75
	v_add_f32_e32 v50, v50, v52
	v_add_f32_e32 v52, v51, v50
	v_pk_mul_f32 v[50:51], v[68:69], v[198:199]
	v_pk_fma_f32 v[32:33], v[32:33], v[156:157], v[154:155] op_sel_hi:[1,0,0]
	v_add_f32_e32 v50, v50, v57
	v_add_f32_e32 v50, v51, v50
	v_add_f32_dpp v51, v52, v52 quad_perm:[1,0,3,2] row_mask:0xf bank_mask:0xf bound_ctrl:1
	v_mov_b32_e32 v55, v53
	v_add_f32_dpp v50, v50, v50 quad_perm:[1,0,3,2] row_mask:0xf bank_mask:0xf bound_ctrl:1
	v_add_f32_dpp v51, v51, v51 quad_perm:[2,3,0,1] row_mask:0xf bank_mask:0xf bound_ctrl:1
	v_mov_b32_e32 v100, v98
	v_add_f32_dpp v50, v50, v50 quad_perm:[2,3,0,1] row_mask:0xf bank_mask:0xf bound_ctrl:1
	v_add_f32_dpp v51, v51, v51 row_ror:4 row_mask:0xf bank_mask:0xf bound_ctrl:1
	v_permlane16_swap_b32_e32 v75, v77
	v_add_f32_dpp v50, v50, v50 row_ror:4 row_mask:0xf bank_mask:0xf bound_ctrl:1
	v_add_f32_dpp v51, v51, v51 row_ror:8 row_mask:0xf bank_mask:0xf bound_ctrl:1
	v_pk_fma_f32 v[32:33], v[36:37], v[158:159], v[32:33] op_sel_hi:[1,0,1]
	v_add_f32_dpp v66, v50, v50 row_ror:8 row_mask:0xf bank_mask:0xf bound_ctrl:1
	v_mov_b32_e32 v68, v66
	s_nop 1
	v_permlane16_swap_b32_e32 v66, v68
	v_pk_fma_f32 v[30:31], v[34:35], v[158:159], v[30:31] op_sel_hi:[1,0,1]
	v_max3_f32 v36, v159, v54, v99
	v_permlane16_swap_b32_e32 v53, v55
	v_permlane16_swap_b32_e32 v98, v100
	v_mov_b32_e32 v76, v74
	v_mov_b32_e32 v67, v51
	v_pk_fma_f32 v[30:31], v[38:39], v[174:175], v[30:31] op_sel_hi:[1,0,1]
	v_max3_f32 v37, v165, v56, v101
	v_max3_f32 v223, v36, v75, v66
	v_permlane16_swap_b32_e32 v74, v76
	v_permlane16_swap_b32_e32 v51, v67
	v_max3_f32 v34, v155, v53, v98
	v_max3_f32 v229, v37, v77, v68
	v_pk_fma_f32 v[26:27], v[26:27], v[208:209], v[30:31] op_sel_hi:[1,0,1]
	v_sub_f32_e32 v31, v159, v223
	v_pk_fma_f32 v[32:33], v[40:41], v[174:175], v[32:33] op_sel_hi:[1,0,1]
	v_max3_f32 v35, v157, v55, v100
	v_max3_f32 v39, v34, v74, v51
	v_exp_f32_e32 v52, v31
	v_sub_f32_e32 v31, v165, v229
	v_max3_f32 v41, v35, v76, v67
	v_pk_fma_f32 v[28:29], v[28:29], v[208:209], v[32:33] op_sel_hi:[1,0,1]
	v_exp_f32_e32 v32, v31
	v_sub_f32_e32 v31, v53, v39
	v_exp_f32_e32 v34, v31
	v_sub_f32_e32 v31, v55, v41
	v_exp_f32_e32 v36, v31
	v_sub_f32_e32 v31, v54, v223
	v_sub_f32_e32 v33, v56, v229
	v_exp_f32_e32 v40, v31
	v_exp_f32_e32 v38, v33
	v_sub_f32_e32 v30, v155, v39
	v_mov_b32_e32 v33, v34
	v_pk_mul_f32 v[54:55], v[64:65], v[34:35] op_sel_hi:[1,0]
	v_pk_mul_f32 v[56:57], v[62:63], v[34:35] op_sel_hi:[1,0]
	v_mov_b32_e32 v53, v36
	v_pk_mul_f32 v[34:35], v[64:65], v[36:37] op_sel_hi:[1,0]
	v_pk_mul_f32 v[36:37], v[62:63], v[36:37] op_sel_hi:[1,0]
	v_mov_b32_e32 v62, v40
	v_pk_mul_f32 v[206:207], v[60:61], v[40:41] op_sel_hi:[1,0]
	v_pk_mul_f32 v[208:209], v[58:59], v[40:41] op_sel_hi:[1,0]
	v_sub_f32_e32 v40, v99, v223
	v_exp_f32_e32 v50, v30
	v_sub_f32_e32 v30, v157, v41
	v_fma_f32 v31, v173, v32, v38
	v_pk_mul_f32 v[224:225], v[60:61], v[38:39] op_sel_hi:[1,0]
	v_pk_mul_f32 v[226:227], v[58:59], v[38:39] op_sel_hi:[1,0]
	v_sub_f32_e32 v38, v98, v39
	v_exp_f32_e32 v212, v40
	v_sub_f32_e32 v40, v101, v229
	v_sub_f32_e32 v51, v51, v39
	v_exp_f32_e32 v30, v30
	v_exp_f32_e32 v210, v38
	v_sub_f32_e32 v38, v100, v41
	v_exp_f32_e32 v228, v40
	v_sub_f32_e32 v40, v74, v39
	v_sub_f32_e32 v59, v75, v223
	v_exp_f32_e32 v236, v51
	v_sub_f32_e32 v51, v67, v41
	v_exp_f32_e32 v38, v38
	v_exp_f32_e32 v230, v40
	v_sub_f32_e32 v40, v76, v41
	v_exp_f32_e32 v232, v59
	v_sub_f32_e32 v59, v77, v229
	v_exp_f32_e32 v238, v51
	v_sub_f32_e32 v51, v66, v223
	v_exp_f32_e32 v40, v40
	v_exp_f32_e32 v234, v59
	v_exp_f32_e32 v240, v51
	v_sub_f32_e32 v51, v68, v229
	v_exp_f32_e32 v242, v51
	v_fmac_f32_e32 v33, v167, v50
	v_fmac_f32_e32 v53, v169, v30
	v_fmac_f32_e32 v62, v171, v52
	v_add_f32_e32 v33, v210, v33
	v_add_f32_e32 v53, v38, v53
	v_add_f32_e32 v58, v212, v62
	v_add_f32_e32 v31, v228, v31
	s_add_u32 s50, s80, s50
	v_add_f32_e32 v33, v230, v33
	v_add_f32_e32 v53, v40, v53
	v_add_f32_e32 v58, v232, v58
	v_add_f32_e32 v31, v234, v31
	s_addc_u32 s51, s81, s51
	v_add_f32_e32 v51, v236, v33
	v_add_f32_e32 v53, v238, v53
	v_add_f32_e32 v231, v240, v58
	v_add_f32_e32 v31, v242, v31
	s_add_u32 s52, s58, s20
	s_addc_u32 s53, s59, s21
	global_load_dwordx4 v[118:121], v186, s[52:53] nt
	global_load_dwordx4 v[114:117], v186, s[52:53] offset:1024 nt
	s_add_u32 s52, s56, s20
	s_addc_u32 s53, s57, s21
	s_add_i32 m0, s98, 0x1000
	s_nop 0
	global_load_lds_dwordx4 v186, s[52:53] nt
	global_load_dwordx4 v[58:61], v186, s[52:53] offset:1024 nt
	s_add_u32 s52, s58, s22
	s_addc_u32 s53, s59, s23
	global_load_dwordx4 v[102:105], v186, s[52:53] nt
	global_load_dwordx4 v[98:101], v186, s[52:53] offset:1024 nt
	s_add_u32 s52, s56, s22
	s_addc_u32 s53, s57, s23
	s_add_i32 m0, s98, 0x1400
	s_nop 0
	global_load_lds_dwordx4 v186, s[52:53] nt
	global_load_dwordx4 v[166:169], v186, s[52:53] offset:1024 nt
	s_add_u32 s52, s58, s24
	s_addc_u32 s53, s59, s25
	global_load_dwordx4 v[78:81], v186, s[52:53] nt
	global_load_dwordx4 v[74:77], v186, s[52:53] offset:1024 nt
	s_add_u32 s52, s56, s24
	s_addc_u32 s53, s57, s25
	s_add_i32 m0, s98, 0x1800
	s_nop 0
	global_load_lds_dwordx4 v186, s[52:53] nt
	global_load_dwordx4 v[158:161], v186, s[52:53] offset:1024 nt
	s_add_u32 s52, s58, s28
	s_addc_u32 s53, s59, s29
	global_load_dwordx4 v[70:73], v186, s[52:53] nt
	global_load_dwordx4 v[66:69], v186, s[52:53] offset:1024 nt
	s_add_u32 s52, s56, s28
	s_addc_u32 s53, s57, s29
	s_add_i32 m0, s98, 0x1c00
	s_nop 0
	global_load_lds_dwordx4 v186, s[52:53] nt
	global_load_dwordx4 v[154:157], v186, s[52:53] offset:1024 nt
	v_pk_fma_f32 v[48:49], v[48:49], v[50:51], v[56:57] op_sel_hi:[1,0,1]
	v_pk_fma_f32 v[46:47], v[46:47], v[50:51], v[54:55] op_sel_hi:[1,0,1]
	v_pk_fma_f32 v[42:43], v[42:43], v[52:53], v[208:209] op_sel_hi:[1,0,1]
	v_pk_fma_f32 v[44:45], v[44:45], v[52:53], v[206:207] op_sel_hi:[1,0,1]
	v_pk_fma_f32 v[46:47], v[16:17], v[210:211], v[46:47] op_sel_hi:[1,0,1]
	v_pk_fma_f32 v[48:49], v[14:15], v[210:211], v[48:49] op_sel_hi:[1,0,1]
	v_pk_fma_f32 v[44:45], v[24:25], v[212:213], v[44:45] op_sel_hi:[1,0,1]
	v_pk_fma_f32 v[42:43], v[22:23], v[212:213], v[42:43] op_sel_hi:[1,0,1]
	v_pk_fma_f32 v[48:49], v[10:11], v[230:231], v[48:49] op_sel_hi:[1,0,1]
	v_pk_fma_f32 v[46:47], v[12:13], v[230:231], v[46:47] op_sel_hi:[1,0,1]
	v_pk_fma_f32 v[42:43], v[18:19], v[232:233], v[42:43] op_sel_hi:[1,0,1]
	v_pk_fma_f32 v[44:45], v[20:21], v[232:233], v[44:45] op_sel_hi:[1,0,1]
	v_pk_fma_f32 v[206:207], v[4:5], v[236:237], v[46:47] op_sel_hi:[1,0,1]
	v_pk_fma_f32 v[208:209], v[2:3], v[236:237], v[48:49] op_sel_hi:[1,0,1]
	v_pk_fma_f32 v[210:211], v[8:9], v[240:241], v[44:45] op_sel_hi:[1,0,1]
	v_pk_fma_f32 v[212:213], v[6:7], v[240:241], v[42:43] op_sel_hi:[1,0,1]
	s_waitcnt vmcnt(31)
	v_mul_f32_e32 v33, v222, v183
	v_fmac_f32_e32 v33, v221, v182
	v_pk_mul_f32 v[42:43], v[184:185], v[200:201]
	s_waitcnt vmcnt(30)
	v_mul_f32_e32 v44, v220, v179
	v_add_f32_e32 v33, v42, v33
	v_add_f32_e32 v33, v43, v33
	v_fmac_f32_e32 v44, v219, v178
	v_pk_mul_f32 v[42:43], v[180:181], v[198:199]
	v_add_f32_dpp v33, v33, v33 quad_perm:[1,0,3,2] row_mask:0xf bank_mask:0xf bound_ctrl:1
	v_add_f32_e32 v42, v42, v44
	v_add_f32_e32 v42, v43, v42
	v_add_f32_dpp v33, v33, v33 quad_perm:[2,3,0,1] row_mask:0xf bank_mask:0xf bound_ctrl:1
	s_waitcnt vmcnt(26)
	v_mul_f32_e32 v48, v220, v123
	v_fmac_f32_e32 v48, v219, v122
	v_add_f32_dpp v33, v33, v33 row_ror:4 row_mask:0xf bank_mask:0xf bound_ctrl:1
	s_waitcnt vmcnt(22)
	v_mul_f32_e32 v54, v220, v107
	v_fmac_f32_e32 v54, v219, v106
	v_add_f32_dpp v44, v33, v33 row_ror:8 row_mask:0xf bank_mask:0xf bound_ctrl:1
	v_add_f32_dpp v33, v42, v42 quad_perm:[1,0,3,2] row_mask:0xf bank_mask:0xf bound_ctrl:1
	v_pk_mul_f32 v[42:43], v[128:129], v[200:201]
	s_waitcnt vmcnt(18)
	v_mul_f32_e32 v91, v220, v91
	v_add_f32_dpp v33, v33, v33 quad_perm:[2,3,0,1] row_mask:0xf bank_mask:0xf bound_ctrl:1
	v_fmac_f32_e32 v91, v219, v90
	v_mov_b32_e32 v46, v44
	v_add_f32_dpp v33, v33, v33 row_ror:4 row_mask:0xf bank_mask:0xf bound_ctrl:1
	s_nop 0
	v_permlane16_swap_b32_e32 v44, v46
	v_add_f32_dpp v45, v33, v33 row_ror:8 row_mask:0xf bank_mask:0xf bound_ctrl:1
	v_mul_f32_e32 v33, v222, v127
	v_fmac_f32_e32 v33, v221, v126
	v_add_f32_e32 v33, v42, v33
	v_add_f32_e32 v33, v43, v33
	v_pk_mul_f32 v[42:43], v[124:125], v[198:199]
	v_mov_b32_e32 v47, v45
	v_add_f32_dpp v33, v33, v33 quad_perm:[1,0,3,2] row_mask:0xf bank_mask:0xf bound_ctrl:1
	v_add_f32_e32 v42, v42, v48
	v_add_f32_e32 v42, v43, v42
	v_add_f32_dpp v33, v33, v33 quad_perm:[2,3,0,1] row_mask:0xf bank_mask:0xf bound_ctrl:1
	v_permlane16_swap_b32_e32 v45, v47
	s_nop 0
	v_add_f32_dpp v33, v33, v33 row_ror:4 row_mask:0xf bank_mask:0xf bound_ctrl:1
	s_nop 1
	v_add_f32_dpp v48, v33, v33 row_ror:8 row_mask:0xf bank_mask:0xf bound_ctrl:1
	v_add_f32_dpp v33, v42, v42 quad_perm:[1,0,3,2] row_mask:0xf bank_mask:0xf bound_ctrl:1
	v_pk_mul_f32 v[42:43], v[112:113], v[200:201]
	v_mov_b32_e32 v50, v48
	v_add_f32_dpp v33, v33, v33 quad_perm:[2,3,0,1] row_mask:0xf bank_mask:0xf bound_ctrl:1
	s_nop 0
	v_permlane16_swap_b32_e32 v48, v50
	v_add_f32_dpp v33, v33, v33 row_ror:4 row_mask:0xf bank_mask:0xf bound_ctrl:1
	s_nop 1
	v_add_f32_dpp v49, v33, v33 row_ror:8 row_mask:0xf bank_mask:0xf bound_ctrl:1
	v_mul_f32_e32 v33, v222, v111
	v_fmac_f32_e32 v33, v221, v110
	v_add_f32_e32 v33, v42, v33
	v_add_f32_e32 v33, v43, v33
	v_pk_mul_f32 v[42:43], v[108:109], v[198:199]
	v_mov_b32_e32 v52, v49
	v_add_f32_dpp v33, v33, v33 quad_perm:[1,0,3,2] row_mask:0xf bank_mask:0xf bound_ctrl:1
	v_add_f32_e32 v42, v42, v54
	v_add_f32_e32 v42, v43, v42
	v_add_f32_dpp v33, v33, v33 quad_perm:[2,3,0,1] row_mask:0xf bank_mask:0xf bound_ctrl:1
	v_permlane16_swap_b32_e32 v49, v52
	s_nop 0
	v_add_f32_dpp v33, v33, v33 row_ror:4 row_mask:0xf bank_mask:0xf bound_ctrl:1
	s_nop 1
	v_add_f32_dpp v54, v33, v33 row_ror:8 row_mask:0xf bank_mask:0xf bound_ctrl:1
	v_add_f32_dpp v33, v42, v42 quad_perm:[1,0,3,2] row_mask:0xf bank_mask:0xf bound_ctrl:1
	v_pk_mul_f32 v[42:43], v[96:97], v[200:201]
	v_mov_b32_e32 v56, v54
	v_add_f32_dpp v33, v33, v33 quad_perm:[2,3,0,1] row_mask:0xf bank_mask:0xf bound_ctrl:1
	s_nop 0
	v_permlane16_swap_b32_e32 v54, v56
	v_add_f32_dpp v33, v33, v33 row_ror:4 row_mask:0xf bank_mask:0xf bound_ctrl:1
	s_nop 1
	v_add_f32_dpp v55, v33, v33 row_ror:8 row_mask:0xf bank_mask:0xf bound_ctrl:1
	v_mul_f32_e32 v33, v222, v95
	v_fmac_f32_e32 v33, v221, v94
	v_add_f32_e32 v33, v42, v33
	v_add_f32_e32 v33, v43, v33
	v_pk_mul_f32 v[42:43], v[92:93], v[198:199]
	v_mov_b32_e32 v57, v55
	v_add_f32_dpp v33, v33, v33 quad_perm:[1,0,3,2] row_mask:0xf bank_mask:0xf bound_ctrl:1
	v_add_f32_e32 v42, v42, v91
	v_add_f32_e32 v42, v43, v42
	v_add_f32_dpp v33, v33, v33 quad_perm:[2,3,0,1] row_mask:0xf bank_mask:0xf bound_ctrl:1
	v_permlane16_swap_b32_e32 v55, v57
	s_nop 0
	v_add_f32_dpp v33, v33, v33 row_ror:4 row_mask:0xf bank_mask:0xf bound_ctrl:1
	s_nop 1
	v_add_f32_dpp v90, v33, v33 row_ror:8 row_mask:0xf bank_mask:0xf bound_ctrl:1
	v_add_f32_dpp v33, v42, v42 quad_perm:[1,0,3,2] row_mask:0xf bank_mask:0xf bound_ctrl:1
	v_mov_b32_e32 v92, v90
	s_nop 1
	v_permlane16_swap_b32_e32 v90, v92
	v_add_f32_dpp v33, v33, v33 quad_perm:[2,3,0,1] row_mask:0xf bank_mask:0xf bound_ctrl:1
	s_nop 1
	v_add_f32_dpp v33, v33, v33 row_ror:4 row_mask:0xf bank_mask:0xf bound_ctrl:1
	v_pk_fma_f32 v[42:43], v[204:205], v[32:33], v[226:227] op_sel_hi:[1,0,1]
	s_nop 0
	v_pk_fma_f32 v[22:23], v[22:23], v[228:229], v[42:43] op_sel_hi:[1,0,1]
	v_add_f32_dpp v91, v33, v33 row_ror:8 row_mask:0xf bank_mask:0xf bound_ctrl:1
	v_pk_fma_f32 v[32:33], v[202:203], v[32:33], v[224:225] op_sel_hi:[1,0,1]
	v_pk_fma_f32 v[18:19], v[18:19], v[234:235], v[22:23] op_sel_hi:[1,0,1]
	v_pk_fma_f32 v[24:25], v[24:25], v[228:229], v[32:33] op_sel_hi:[1,0,1]
	v_pk_fma_f32 v[6:7], v[6:7], v[242:243], v[18:19] op_sel_hi:[1,0,1]
	v_max3_f32 v18, v39, v44, v48
	v_max3_f32 v19, v41, v46, v50
	v_mov_b32_e32 v93, v91
	v_pk_fma_f32 v[20:21], v[20:21], v[234:235], v[24:25] op_sel_hi:[1,0,1]
	v_max3_f32 v225, v18, v54, v90
	v_max3_f32 v227, v19, v56, v92
	v_pk_fma_f32 v[18:19], v[26:27], v[30:31], v[36:37] op_sel_hi:[1,0,1]
	v_permlane16_swap_b32_e32 v91, v93
	v_pk_fma_f32 v[8:9], v[8:9], v[242:243], v[20:21] op_sel_hi:[1,0,1]
	v_max3_f32 v20, v223, v45, v49
	v_max3_f32 v21, v229, v47, v52
	v_pk_fma_f32 v[14:15], v[14:15], v[38:39], v[18:19] op_sel_hi:[1,0,1]
	v_max3_f32 v233, v20, v55, v91
	v_max3_f32 v235, v21, v57, v93
	v_pk_fma_f32 v[20:21], v[28:29], v[30:31], v[34:35] op_sel_hi:[1,0,1]
	v_pk_fma_f32 v[10:11], v[10:11], v[40:41], v[14:15] op_sel_hi:[1,0,1]
	v_pk_fma_f32 v[16:17], v[16:17], v[38:39], v[20:21] op_sel_hi:[1,0,1]
	v_pk_fma_f32 v[2:3], v[2:3], v[238:239], v[10:11] op_sel_hi:[1,0,1]
	v_sub_f32_e32 v11, v223, v233
	v_pk_fma_f32 v[12:13], v[12:13], v[40:41], v[16:17] op_sel_hi:[1,0,1]
	v_exp_f32_e32 v24, v11
	v_sub_f32_e32 v11, v229, v235
	v_pk_fma_f32 v[4:5], v[4:5], v[238:239], v[12:13] op_sel_hi:[1,0,1]
	v_exp_f32_e32 v12, v11
	v_sub_f32_e32 v11, v44, v225
	v_exp_f32_e32 v14, v11
	v_sub_f32_e32 v11, v46, v227
	v_exp_f32_e32 v16, v11
	v_sub_f32_e32 v11, v45, v233
	v_sub_f32_e32 v10, v39, v225
	v_exp_f32_e32 v20, v11
	v_exp_f32_e32 v22, v10
	v_sub_f32_e32 v10, v41, v227
	v_exp_f32_e32 v10, v10
	v_sub_f32_e32 v13, v47, v235
	v_exp_f32_e32 v18, v13
	v_mov_b32_e32 v21, v20
	v_mov_b32_e32 v19, v16
	v_fmac_f32_e32 v21, v231, v24
	v_sub_f32_e32 v23, v55, v233
	v_fmac_f32_e32 v19, v53, v10
	v_pk_mul_f32 v[182:183], v[84:85], v[20:21] op_sel_hi:[1,0]
	v_pk_mul_f32 v[184:185], v[82:83], v[20:21] op_sel_hi:[1,0]
	v_sub_f32_e32 v20, v49, v233
	v_exp_f32_e32 v232, v23
	v_sub_f32_e32 v23, v57, v235
	v_fma_f32 v11, v31, v12, v18
	v_pk_mul_f32 v[202:203], v[84:85], v[18:19] op_sel_hi:[1,0]
	v_pk_mul_f32 v[204:205], v[82:83], v[18:19] op_sel_hi:[1,0]
	v_sub_f32_e32 v18, v48, v225
	v_exp_f32_e32 v226, v20
	v_sub_f32_e32 v20, v52, v235
	v_exp_f32_e32 v234, v23
	v_sub_f32_e32 v23, v90, v225
	v_exp_f32_e32 v224, v18
	v_sub_f32_e32 v18, v50, v227
	v_exp_f32_e32 v228, v20
	v_sub_f32_e32 v20, v54, v225
	v_exp_f32_e32 v236, v23
	v_sub_f32_e32 v23, v92, v227
	v_exp_f32_e32 v18, v18
	v_exp_f32_e32 v230, v20
	v_sub_f32_e32 v20, v56, v227
	v_exp_f32_e32 v238, v23
	v_sub_f32_e32 v23, v91, v233
	v_exp_f32_e32 v20, v20
	v_exp_f32_e32 v240, v23
	v_sub_f32_e32 v23, v93, v235
	v_mov_b32_e32 v13, v14
	v_exp_f32_e32 v242, v23
	v_fmac_f32_e32 v13, v51, v22
	v_add_f32_e32 v13, v224, v13
	v_add_f32_e32 v19, v18, v19
	v_add_f32_e32 v21, v226, v21
	v_add_f32_e32 v11, v228, v11
	v_add_f32_e32 v13, v230, v13
	v_add_f32_e32 v19, v20, v19
	v_add_f32_e32 v21, v232, v21
	v_add_f32_e32 v11, v234, v11
	s_waitcnt vmcnt(17)
	ds_read_b128 v[86:89], v246 offset:0
	ds_read_b128 v[130:133], v246 offset:1024
	ds_read_b128 v[134:137], v246 offset:2048
	ds_read_b128 v[138:141], v246 offset:3072
	s_waitcnt lgkmcnt(0)
	v_pk_mul_f32 v[178:179], v[88:89], v[14:15] op_sel_hi:[1,0]
	v_pk_mul_f32 v[180:181], v[86:87], v[14:15] op_sel_hi:[1,0]
	v_pk_mul_f32 v[14:15], v[88:89], v[16:17] op_sel_hi:[1,0]
	v_pk_mul_f32 v[16:17], v[86:87], v[16:17] op_sel_hi:[1,0]
	v_add_f32_e32 v13, v236, v13
	v_add_f32_e32 v19, v238, v19
	v_add_f32_e32 v21, v240, v21
	v_add_f32_e32 v11, v242, v11
	s_add_u32 s52, s8, s30
	s_addc_u32 s53, s9, s31
	global_load_dwordx4 v[126:129], v186, s[52:53] nt
	global_load_dwordx4 v[122:125], v186, s[52:53] offset:1024 nt
	s_add_u32 s52, s50, s30
	s_addc_u32 s53, s51, s31
	s_add_i32 m0, s98, 0x0
	s_nop 0
	global_load_lds_dwordx4 v186, s[52:53] nt
	global_load_dwordx4 v[54:57], v186, s[52:53] offset:1024 nt
	s_add_u32 s52, s8, s36
	s_addc_u32 s53, s9, s37
	global_load_dwordx4 v[110:113], v186, s[52:53] nt
	global_load_dwordx4 v[106:109], v186, s[52:53] offset:1024 nt
	s_add_u32 s52, s50, s36
	s_addc_u32 s53, s51, s37
	s_add_i32 m0, s98, 0x400
	s_nop 0
	global_load_lds_dwordx4 v186, s[52:53] nt
	global_load_dwordx4 v[50:53], v186, s[52:53] offset:1024 nt
	s_add_u32 s52, s8, s38
	s_addc_u32 s53, s9, s39
	global_load_dwordx4 v[94:97], v186, s[52:53] nt
	global_load_dwordx4 v[90:93], v186, s[52:53] offset:1024 nt
	s_add_u32 s52, s50, s38
	s_addc_u32 s53, s51, s39
	s_add_i32 m0, s98, 0x800
	s_nop 0
	global_load_lds_dwordx4 v186, s[52:53] nt
	global_load_dwordx4 v[46:49], v186, s[52:53] offset:1024 nt
	s_add_u32 s52, s8, s40
	s_addc_u32 s53, s9, s41
	global_load_dwordx4 v[86:89], v186, s[52:53] nt
	global_load_dwordx4 v[82:85], v186, s[52:53] offset:1024 nt
	s_add_u32 s52, s50, s40
	s_addc_u32 s53, s51, s41
	s_add_i32 m0, s98, 0xc00
	s_nop 0
	global_load_lds_dwordx4 v186, s[52:53] nt
	global_load_dwordx4 v[42:45], v186, s[52:53] offset:1024 nt
	v_pk_fma_f32 v[180:181], v[208:209], v[22:23], v[180:181] op_sel_hi:[1,0,1]
	v_pk_fma_f32 v[22:23], v[206:207], v[22:23], v[178:179] op_sel_hi:[1,0,1]
	v_pk_fma_f32 v[178:179], v[212:213], v[24:25], v[184:185] op_sel_hi:[1,0,1]
	v_pk_fma_f32 v[24:25], v[210:211], v[24:25], v[182:183] op_sel_hi:[1,0,1]
	v_pk_fma_f32 v[22:23], v[132:133], v[224:225], v[22:23] op_sel_hi:[1,0,1]
	v_pk_fma_f32 v[180:181], v[130:131], v[224:225], v[180:181] op_sel_hi:[1,0,1]
	v_pk_fma_f32 v[24:25], v[144:145], v[226:227], v[24:25] op_sel_hi:[1,0,1]
	v_pk_fma_f32 v[178:179], v[142:143], v[226:227], v[178:179] op_sel_hi:[1,0,1]
	v_pk_fma_f32 v[182:183], v[134:135], v[230:231], v[180:181] op_sel_hi:[1,0,1]
	v_pk_fma_f32 v[22:23], v[136:137], v[230:231], v[22:23] op_sel_hi:[1,0,1]
	v_pk_fma_f32 v[206:207], v[146:147], v[232:233], v[178:179] op_sel_hi:[1,0,1]
	v_pk_fma_f32 v[24:25], v[148:149], v[232:233], v[24:25] op_sel_hi:[1,0,1]
	s_waitcnt vmcnt(33)
	v_pk_fma_f32 v[180:181], v[140:141], v[236:237], v[22:23] op_sel_hi:[1,0,1]
	v_pk_fma_f32 v[184:185], v[138:139], v[236:237], v[182:183] op_sel_hi:[1,0,1]
	s_waitcnt vmcnt(32)
	v_pk_fma_f32 v[178:179], v[152:153], v[240:241], v[24:25] op_sel_hi:[1,0,1]
	v_pk_fma_f32 v[182:183], v[150:151], v[240:241], v[206:207] op_sel_hi:[1,0,1]
	s_waitcnt vmcnt(31)
	v_mul_f32_e32 v24, v222, v119
	v_fmac_f32_e32 v24, v221, v118
	v_pk_mul_f32 v[22:23], v[120:121], v[200:201]
	s_waitcnt vmcnt(30)
	v_mul_f32_e32 v25, v220, v115
	v_add_f32_e32 v22, v22, v24
	v_add_f32_e32 v24, v23, v22
	v_fmac_f32_e32 v25, v219, v114
	v_pk_mul_f32 v[22:23], v[116:117], v[198:199]
	s_waitcnt vmcnt(27)
	v_mul_f32_e32 v103, v222, v103
	v_add_f32_e32 v22, v22, v25
	v_add_f32_e32 v22, v23, v22
	v_add_f32_dpp v23, v24, v24 quad_perm:[1,0,3,2] row_mask:0xf bank_mask:0xf bound_ctrl:1
	v_fmac_f32_e32 v103, v221, v102
	v_add_f32_dpp v22, v22, v22 quad_perm:[1,0,3,2] row_mask:0xf bank_mask:0xf bound_ctrl:1
	v_add_f32_dpp v23, v23, v23 quad_perm:[2,3,0,1] row_mask:0xf bank_mask:0xf bound_ctrl:1
	s_waitcnt vmcnt(26)
	v_mul_f32_e32 v99, v220, v99
	v_add_f32_dpp v22, v22, v22 quad_perm:[2,3,0,1] row_mask:0xf bank_mask:0xf bound_ctrl:1
	v_add_f32_dpp v23, v23, v23 row_ror:4 row_mask:0xf bank_mask:0xf bound_ctrl:1
	v_fmac_f32_e32 v99, v219, v98
	v_add_f32_dpp v22, v22, v22 row_ror:4 row_mask:0xf bank_mask:0xf bound_ctrl:1
	v_add_f32_dpp v24, v23, v23 row_ror:8 row_mask:0xf bank_mask:0xf bound_ctrl:1
	s_waitcnt vmcnt(23)
	v_mul_f32_e32 v79, v222, v79
	v_add_f32_dpp v25, v22, v22 row_ror:8 row_mask:0xf bank_mask:0xf bound_ctrl:1
	v_pk_mul_f32 v[22:23], v[104:105], v[200:201]
	v_fmac_f32_e32 v79, v221, v78
	v_add_f32_e32 v22, v22, v103
	v_add_f32_e32 v102, v23, v22
	v_pk_mul_f32 v[22:23], v[100:101], v[198:199]
	s_waitcnt vmcnt(22)
	v_mul_f32_e32 v75, v220, v75
	v_add_f32_e32 v22, v22, v99
	v_add_f32_e32 v22, v23, v22
	v_add_f32_dpp v23, v102, v102 quad_perm:[1,0,3,2] row_mask:0xf bank_mask:0xf bound_ctrl:1
	v_fmac_f32_e32 v75, v219, v74
	v_add_f32_dpp v22, v22, v22 quad_perm:[1,0,3,2] row_mask:0xf bank_mask:0xf bound_ctrl:1
	v_add_f32_dpp v23, v23, v23 quad_perm:[2,3,0,1] row_mask:0xf bank_mask:0xf bound_ctrl:1
	s_waitcnt vmcnt(19)
	v_mul_f32_e32 v71, v222, v71
	v_add_f32_dpp v22, v22, v22 quad_perm:[2,3,0,1] row_mask:0xf bank_mask:0xf bound_ctrl:1
	v_add_f32_dpp v23, v23, v23 row_ror:4 row_mask:0xf bank_mask:0xf bound_ctrl:1
	v_fmac_f32_e32 v71, v221, v70
	v_add_f32_dpp v22, v22, v22 row_ror:4 row_mask:0xf bank_mask:0xf bound_ctrl:1
	v_add_f32_dpp v98, v23, v23 row_ror:8 row_mask:0xf bank_mask:0xf bound_ctrl:1
	s_waitcnt vmcnt(18)
	v_mul_f32_e32 v67, v220, v67
	v_add_f32_dpp v99, v22, v22 row_ror:8 row_mask:0xf bank_mask:0xf bound_ctrl:1
	v_pk_mul_f32 v[22:23], v[80:81], v[200:201]
	v_fmac_f32_e32 v67, v219, v66
	v_add_f32_e32 v22, v22, v79
	v_add_f32_e32 v78, v23, v22
	v_pk_mul_f32 v[22:23], v[76:77], v[198:199]
	v_pk_fma_f32 v[6:7], v[6:7], v[12:13], v[204:205] op_sel_hi:[1,0,1]
	v_add_f32_e32 v22, v22, v75
	v_add_f32_e32 v22, v23, v22
	v_add_f32_dpp v23, v78, v78 quad_perm:[1,0,3,2] row_mask:0xf bank_mask:0xf bound_ctrl:1
	v_mov_b32_e32 v114, v24
	v_add_f32_dpp v22, v22, v22 quad_perm:[1,0,3,2] row_mask:0xf bank_mask:0xf bound_ctrl:1
	v_add_f32_dpp v23, v23, v23 quad_perm:[2,3,0,1] row_mask:0xf bank_mask:0xf bound_ctrl:1
	v_mov_b32_e32 v100, v98
	v_add_f32_dpp v22, v22, v22 quad_perm:[2,3,0,1] row_mask:0xf bank_mask:0xf bound_ctrl:1
	v_add_f32_dpp v23, v23, v23 row_ror:4 row_mask:0xf bank_mask:0xf bound_ctrl:1
	v_pk_fma_f32 v[8:9], v[8:9], v[12:13], v[202:203] op_sel_hi:[1,0,1]
	v_add_f32_dpp v22, v22, v22 row_ror:4 row_mask:0xf bank_mask:0xf bound_ctrl:1
	v_add_f32_dpp v74, v23, v23 row_ror:8 row_mask:0xf bank_mask:0xf bound_ctrl:1
	v_pk_fma_f32 v[6:7], v[142:143], v[228:229], v[6:7] op_sel_hi:[1,0,1]
	v_add_f32_dpp v75, v22, v22 row_ror:8 row_mask:0xf bank_mask:0xf bound_ctrl:1
	v_pk_mul_f32 v[22:23], v[72:73], v[200:201]
	v_permlane16_swap_b32_e32 v24, v114
	v_add_f32_e32 v22, v22, v71
	v_add_f32_e32 v70, v23, v22
	v_pk_mul_f32 v[22:23], v[68:69], v[198:199]
	v_permlane16_swap_b32_e32 v98, v100
	v_add_f32_e32 v22, v22, v67
	v_add_f32_e32 v22, v23, v22
	v_add_f32_dpp v23, v70, v70 quad_perm:[1,0,3,2] row_mask:0xf bank_mask:0xf bound_ctrl:1
	v_mov_b32_e32 v76, v74
	v_add_f32_dpp v22, v22, v22 quad_perm:[1,0,3,2] row_mask:0xf bank_mask:0xf bound_ctrl:1
	v_add_f32_dpp v23, v23, v23 quad_perm:[2,3,0,1] row_mask:0xf bank_mask:0xf bound_ctrl:1
	v_pk_fma_f32 v[8:9], v[144:145], v[228:229], v[8:9] op_sel_hi:[1,0,1]
	v_add_f32_dpp v22, v22, v22 quad_perm:[2,3,0,1] row_mask:0xf bank_mask:0xf bound_ctrl:1
	v_add_f32_dpp v23, v23, v23 row_ror:4 row_mask:0xf bank_mask:0xf bound_ctrl:1
	v_pk_fma_f32 v[6:7], v[146:147], v[234:235], v[6:7] op_sel_hi:[1,0,1]
	v_add_f32_dpp v22, v22, v22 row_ror:4 row_mask:0xf bank_mask:0xf bound_ctrl:1
	v_add_f32_dpp v23, v23, v23 row_ror:8 row_mask:0xf bank_mask:0xf bound_ctrl:1
	v_mov_b32_e32 v66, v23
	v_pk_fma_f32 v[2:3], v[2:3], v[10:11], v[16:17] op_sel_hi:[1,0,1]
	v_mov_b32_e32 v115, v25
	v_mov_b32_e32 v101, v99
	v_permlane16_swap_b32_e32 v74, v76
	v_add_f32_dpp v22, v22, v22 row_ror:8 row_mask:0xf bank_mask:0xf bound_ctrl:1
	v_permlane16_swap_b32_e32 v23, v66
	v_pk_fma_f32 v[8:9], v[148:149], v[234:235], v[8:9] op_sel_hi:[1,0,1]
	v_pk_fma_f32 v[148:149], v[150:151], v[242:243], v[6:7] op_sel_hi:[1,0,1]
	v_max3_f32 v6, v225, v24, v98
	v_pk_fma_f32 v[4:5], v[4:5], v[10:11], v[14:15] op_sel_hi:[1,0,1]
	v_pk_fma_f32 v[2:3], v[130:131], v[18:19], v[2:3] op_sel_hi:[1,0,1]
	v_permlane16_swap_b32_e32 v25, v115
	v_permlane16_swap_b32_e32 v99, v101
	v_mov_b32_e32 v77, v75
	v_mov_b32_e32 v67, v22
	v_max3_f32 v7, v227, v114, v100
	v_max3_f32 v142, v6, v74, v23
	v_pk_fma_f32 v[4:5], v[132:133], v[18:19], v[4:5] op_sel_hi:[1,0,1]
	v_pk_fma_f32 v[2:3], v[134:135], v[20:21], v[2:3] op_sel_hi:[1,0,1]
	v_permlane16_swap_b32_e32 v75, v77
	v_permlane16_swap_b32_e32 v22, v67
	v_pk_fma_f32 v[146:147], v[152:153], v[242:243], v[8:9] op_sel_hi:[1,0,1]
	v_max3_f32 v8, v233, v25, v99
	v_max3_f32 v144, v7, v76, v66
	v_pk_fma_f32 v[4:5], v[136:137], v[20:21], v[4:5] op_sel_hi:[1,0,1]
	v_pk_fma_f32 v[136:137], v[138:139], v[238:239], v[2:3] op_sel_hi:[1,0,1]
	v_sub_f32_e32 v2, v225, v142
	v_max3_f32 v9, v235, v115, v101
	v_max3_f32 v143, v8, v75, v22
	v_exp_f32_e32 v138, v2
	v_sub_f32_e32 v2, v227, v144
	v_max3_f32 v145, v9, v77, v67
	v_pk_fma_f32 v[134:135], v[140:141], v[238:239], v[4:5] op_sel_hi:[1,0,1]
	v_exp_f32_e32 v140, v2
	v_sub_f32_e32 v2, v233, v143
	v_exp_f32_e32 v150, v2
	v_sub_f32_e32 v2, v235, v145
	v_exp_f32_e32 v152, v2
	v_sub_f32_e32 v2, v24, v142
	v_exp_f32_e32 v2, v2
	v_sub_f32_e32 v4, v115, v145
	v_exp_f32_e32 v4, v4
	v_sub_f32_e32 v3, v114, v144
	v_mov_b32_e32 v5, v2
	v_exp_f32_e32 v6, v3
	v_sub_f32_e32 v3, v25, v143
	v_fmac_f32_e32 v5, v13, v138
	v_exp_f32_e32 v8, v3
	v_fma_f32 v3, v11, v152, v4
	v_pk_mul_f32 v[210:211], v[60:61], v[4:5] op_sel_hi:[1,0]
	v_pk_mul_f32 v[212:213], v[58:59], v[4:5] op_sel_hi:[1,0]
	v_sub_f32_e32 v4, v98, v142
	v_exp_f32_e32 v220, v4
	v_sub_f32_e32 v4, v100, v144
	v_exp_f32_e32 v222, v4
	v_sub_f32_e32 v4, v99, v143
	v_exp_f32_e32 v224, v4
	s_waitcnt vmcnt(17)
	ds_read_b128 v[62:65], v246 offset:4096
	ds_read_b128 v[174:177], v246 offset:5120
	ds_read_b128 v[170:173], v246 offset:6144
	ds_read_b128 v[162:165], v246 offset:7168
	s_waitcnt lgkmcnt(0)
	v_pk_mul_f32 v[198:199], v[64:65], v[2:3] op_sel_hi:[1,0]
	v_pk_mul_f32 v[200:201], v[62:63], v[2:3] op_sel_hi:[1,0]
	v_mov_b32_e32 v2, v6
	v_pk_mul_f32 v[202:203], v[64:65], v[6:7] op_sel_hi:[1,0]
	v_pk_mul_f32 v[204:205], v[62:63], v[6:7] op_sel_hi:[1,0]
	v_mov_b32_e32 v6, v8
	v_fmac_f32_e32 v6, v21, v150
	v_sub_f32_e32 v4, v101, v145
	v_exp_f32_e32 v226, v4
	v_add_f32_e32 v4, v220, v5
	v_add_f32_e32 v5, v224, v6
	v_sub_f32_e32 v6, v74, v142
	v_exp_f32_e32 v228, v6
	v_sub_f32_e32 v6, v76, v144
	v_exp_f32_e32 v230, v6
	v_sub_f32_e32 v6, v75, v143
	v_exp_f32_e32 v232, v6
	v_sub_f32_e32 v6, v77, v145
	v_exp_f32_e32 v234, v6
	v_sub_f32_e32 v6, v23, v142
	v_exp_f32_e32 v236, v6
	v_sub_f32_e32 v6, v66, v144
	v_exp_f32_e32 v238, v6
	v_sub_f32_e32 v6, v22, v143
	v_exp_f32_e32 v240, v6
	v_sub_f32_e32 v6, v67, v145
	v_exp_f32_e32 v242, v6
	v_fmac_f32_e32 v2, v19, v140
	v_add_f32_e32 v2, v222, v2
	v_add_f32_e32 v3, v226, v3
	v_add_f32_e32 v4, v228, v4
	v_add_f32_e32 v2, v230, v2
	v_add_f32_e32 v5, v232, v5
	v_add_f32_e32 v3, v234, v3
	v_add_f32_e32 v130, v236, v4
	v_add_f32_e32 v132, v238, v2
	v_add_f32_e32 v131, v240, v5
	v_add_f32_e32 v133, v242, v3
	v_pk_mul_f32 v[206:207], v[60:61], v[8:9] op_sel_hi:[1,0]
	v_pk_mul_f32 v[208:209], v[58:59], v[8:9] op_sel_hi:[1,0]
	s_add_u32 s52, s8, s42
	s_addc_u32 s53, s9, s43
	global_load_dwordx4 v[118:121], v186, s[52:53] nt
	global_load_dwordx4 v[114:117], v186, s[52:53] offset:1024 nt
	s_add_u32 s52, s50, s42
	s_addc_u32 s53, s51, s43
	s_add_i32 m0, s98, 0x1000
	s_nop 0
	global_load_lds_dwordx4 v186, s[52:53] nt
	global_load_dwordx4 v[58:61], v186, s[52:53] offset:1024 nt
	s_add_u32 s52, s8, s44
	s_addc_u32 s53, s9, s45
	global_load_dwordx4 v[102:105], v186, s[52:53] nt
	global_load_dwordx4 v[98:101], v186, s[52:53] offset:1024 nt
	s_add_u32 s52, s50, s44
	s_addc_u32 s53, s51, s45
	s_add_i32 m0, s98, 0x1400
	s_nop 0
	global_load_lds_dwordx4 v186, s[52:53] nt
	global_load_dwordx4 v[22:25], v186, s[52:53] offset:1024 nt
	s_add_u32 s52, s8, s46
	s_addc_u32 s53, s9, s47
	global_load_dwordx4 v[74:77], v186, s[52:53] nt
	global_load_dwordx4 v[78:81], v186, s[52:53] offset:1024 nt
	s_add_u32 s52, s50, s46
	s_addc_u32 s53, s51, s47
	s_add_i32 m0, s98, 0x1800
	s_nop 0
	global_load_lds_dwordx4 v186, s[52:53] nt
	global_load_dwordx4 v[18:21], v186, s[52:53] offset:1024 nt
	s_add_u32 s52, s8, s48
	s_addc_u32 s53, s9, s49
	global_load_dwordx4 v[70:73], v186, s[52:53] nt
	global_load_dwordx4 v[66:69], v186, s[52:53] offset:1024 nt
	s_add_u32 s52, s50, s48
	s_addc_u32 s53, s51, s49
	s_add_i32 m0, s98, 0x1c00
	s_nop 0
	global_load_lds_dwordx4 v186, s[52:53] nt
	global_load_dwordx4 v[6:9], v186, s[52:53] offset:1024 nt
	v_pk_fma_f32 v[184:185], v[184:185], v[138:139], v[200:201] op_sel_hi:[1,0,1]
	v_pk_fma_f32 v[138:139], v[180:181], v[138:139], v[198:199] op_sel_hi:[1,0,1]
	v_pk_fma_f32 v[136:137], v[136:137], v[140:141], v[204:205] op_sel_hi:[1,0,1]
	v_pk_fma_f32 v[134:135], v[134:135], v[140:141], v[202:203] op_sel_hi:[1,0,1]
	v_pk_fma_f32 v[140:141], v[182:183], v[150:151], v[208:209] op_sel_hi:[1,0,1]
	v_pk_fma_f32 v[150:151], v[178:179], v[150:151], v[206:207] op_sel_hi:[1,0,1]
	v_pk_fma_f32 v[148:149], v[148:149], v[152:153], v[212:213] op_sel_hi:[1,0,1]
	v_pk_fma_f32 v[146:147], v[146:147], v[152:153], v[210:211] op_sel_hi:[1,0,1]
	v_pk_fma_f32 v[138:139], v[176:177], v[220:221], v[138:139] op_sel_hi:[1,0,1]
	v_pk_fma_f32 v[152:153], v[174:175], v[220:221], v[184:185] op_sel_hi:[1,0,1]
	v_pk_fma_f32 v[134:135], v[176:177], v[222:223], v[134:135] op_sel_hi:[1,0,1]
	v_pk_fma_f32 v[136:137], v[174:175], v[222:223], v[136:137] op_sel_hi:[1,0,1]
	v_pk_fma_f32 v[150:151], v[168:169], v[224:225], v[150:151] op_sel_hi:[1,0,1]
	v_pk_fma_f32 v[140:141], v[166:167], v[224:225], v[140:141] op_sel_hi:[1,0,1]
	v_pk_fma_f32 v[146:147], v[168:169], v[226:227], v[146:147] op_sel_hi:[1,0,1]
	v_pk_fma_f32 v[148:149], v[166:167], v[226:227], v[148:149] op_sel_hi:[1,0,1]
	v_pk_fma_f32 v[152:153], v[170:171], v[228:229], v[152:153] op_sel_hi:[1,0,1]
	v_pk_fma_f32 v[138:139], v[172:173], v[228:229], v[138:139] op_sel_hi:[1,0,1]
	v_pk_fma_f32 v[166:167], v[170:171], v[230:231], v[136:137] op_sel_hi:[1,0,1]
	v_pk_fma_f32 v[168:169], v[172:173], v[230:231], v[134:135] op_sel_hi:[1,0,1]
	v_pk_fma_f32 v[170:171], v[158:159], v[232:233], v[140:141] op_sel_hi:[1,0,1]
	v_pk_fma_f32 v[150:151], v[160:161], v[232:233], v[150:151] op_sel_hi:[1,0,1]
	v_pk_fma_f32 v[158:159], v[158:159], v[234:235], v[148:149] op_sel_hi:[1,0,1]
	v_pk_fma_f32 v[160:161], v[160:161], v[234:235], v[146:147] op_sel_hi:[1,0,1]
	s_waitcnt vmcnt(33)
	v_pk_fma_f32 v[136:137], v[164:165], v[236:237], v[138:139] op_sel_hi:[1,0,1]
	v_pk_fma_f32 v[134:135], v[162:163], v[236:237], v[152:153] op_sel_hi:[1,0,1]
	v_pk_fma_f32 v[140:141], v[164:165], v[238:239], v[168:169] op_sel_hi:[1,0,1]
	v_pk_fma_f32 v[138:139], v[162:163], v[238:239], v[166:167] op_sel_hi:[1,0,1]
	s_waitcnt vmcnt(32)
	v_pk_fma_f32 v[148:149], v[156:157], v[240:241], v[150:151] op_sel_hi:[1,0,1]
	v_pk_fma_f32 v[146:147], v[154:155], v[240:241], v[170:171] op_sel_hi:[1,0,1]
	v_pk_fma_f32 v[152:153], v[156:157], v[242:243], v[160:161] op_sel_hi:[1,0,1]
	v_pk_fma_f32 v[150:151], v[154:155], v[242:243], v[158:159] op_sel_hi:[1,0,1]
	ds_write_b128 v1, v[134:137]
	ds_write_b128 v1, v[146:149] offset:1024
	ds_write_b128 v1, v[138:141] offset:2048
	ds_write_b128 v1, v[150:153] offset:3072
	s_and_saveexec_b64 s[52:53], s[2:3]
	s_cbranch_execz .LBB0_888
	v_add_u32_e32 v134, 0x8000, v214
	ds_write2_b32 v134, v142, v144 offset1:1
	v_add_u32_e32 v134, 0x8010, v214
	ds_write2_b32 v134, v143, v145 offset1:1
	v_add_u32_e32 v134, 0x8100, v214
	ds_write2_b32 v134, v130, v132 offset1:1
	v_add_u32_e32 v130, 0x8110, v214
	ds_write2_b32 v130, v131, v133 offset1:1

	.amdhsa_kernel _Z6mk_fwd4Args
		.amdhsa_group_segment_fixed_size 0
		.amdhsa_private_segment_fixed_size 0
		.amdhsa_kernarg_size 472
		.amdhsa_user_sgpr_count 2
		.amdhsa_user_sgpr_dispatch_ptr 0
		.amdhsa_user_sgpr_queue_ptr 0
		.amdhsa_user_sgpr_kernarg_segment_ptr 1
		.amdhsa_user_sgpr_dispatch_id 0
		.amdhsa_user_sgpr_kernarg_preload_length 0
		.amdhsa_user_sgpr_kernarg_preload_offset 0
		.amdhsa_user_sgpr_private_segment_size 0
		.amdhsa_uses_dynamic_stack 0
		.amdhsa_enable_private_segment 0
		.amdhsa_system_sgpr_workgroup_id_x 1
		.amdhsa_system_sgpr_workgroup_id_y 0
		.amdhsa_system_sgpr_workgroup_id_z 0
		.amdhsa_system_sgpr_workgroup_info 0
		.amdhsa_system_vgpr_workitem_id 0
		.amdhsa_next_free_vgpr 248
		.amdhsa_next_free_sgpr 100
		.amdhsa_accum_offset 248
		.amdhsa_reserve_vcc 1
		.amdhsa_float_round_mode_32 0
		.amdhsa_float_round_mode_16_64 0
		.amdhsa_float_denorm_mode_32 3
		.amdhsa_float_denorm_mode_16_64 3
		.amdhsa_dx10_clamp 1
		.amdhsa_ieee_mode 1
		.amdhsa_fp16_overflow 0
		.amdhsa_tg_split 0
		.amdhsa_exception_fp_ieee_invalid_op 0
		.amdhsa_exception_fp_denorm_src 0
		.amdhsa_exception_fp_ieee_div_zero 0
		.amdhsa_exception_fp_ieee_overflow 0
		.amdhsa_exception_fp_ieee_underflow 0
		.amdhsa_exception_fp_ieee_inexact 0
		.amdhsa_exception_int_div_zero 0
	.end_amdhsa_kernel

amdhsa.kernels:
  - .agpr_count:     0
    .args:
      - .offset:         0
        .size:           216
        .value_kind:     by_value
      - .offset:         216
        .size:           4
        .value_kind:     hidden_block_count_x
      - .offset:         220
        .size:           4
        .value_kind:     hidden_block_count_y
      - .offset:         224
        .size:           4
        .value_kind:     hidden_block_count_z
      - .offset:         228
        .size:           2
        .value_kind:     hidden_group_size_x
      - .offset:         230
        .size:           2
        .value_kind:     hidden_group_size_y
      - .offset:         232
        .size:           2
        .value_kind:     hidden_group_size_z
      - .offset:         234
        .size:           2
        .value_kind:     hidden_remainder_x
      - .offset:         236
        .size:           2
        .value_kind:     hidden_remainder_y
      - .offset:         238
        .size:           2
        .value_kind:     hidden_remainder_z
      - .offset:         256
        .size:           8
        .value_kind:     hidden_global_offset_x
      - .offset:         264
        .size:           8
        .value_kind:     hidden_global_offset_y
      - .offset:         272
        .size:           8
        .value_kind:     hidden_global_offset_z
      - .offset:         280
        .size:           2
        .value_kind:     hidden_grid_dims
      - .offset:         336
        .size:           4
        .value_kind:     hidden_dynamic_lds_size
    .group_segment_fixed_size: 0
    .kernarg_segment_align: 8
    .kernarg_segment_size: 472
    .language:       OpenCL C
    .language_version:
      - 2
      - 0
    .max_flat_workgroup_size: 512
    .name:           _Z6mk_fwd4Args
    .private_segment_fixed_size: 0
    .sgpr_count:     106
    .sgpr_spill_count: 175
    .symbol:         _Z6mk_fwd4Args.kd
    .uniform_work_group_size: 1
    .uses_dynamic_stack: false
    .vgpr_count:     248
    .vgpr_spill_count: 0
    .wavefront_size: 64
